# in-proj: MFMA operands swapped (lane = token row, 4 consecutive columns) + epilogue exchanges the two 16-col blocks across lane rows (permlane32/16 swap) -> one 16-byte store per lane, 64 contiguous b
# speedup vs baseline: 1.0107x; 1.0097x over previous
; #define G8_LDA(dst, b, h) for (int m = 0; m < 4; ++m) for (int k = 0; k < 2; ++k) \
;     dst[m][k] = *reinterpret_cast<const bf16x8*>((char*)G8_SA(b, h) + g8_lds_byte(wr * 64 + m * 16 + fr, k * 32 + fq * 8))
; #define G8_LDB(dst, b, h) for (int n = 0; n < 2; ++n) for (int k = 0; k < 2; ++k) \
;     dst[n][k] = *reinterpret_cast<const bf16x8*>((char*)G8_SB(b, h) + g8_lds_byte(wc * 32 + n * 16 + fr, k * 32 + fq * 8))
; #define G8_MMA(ai, bj, At_, Bt_) do { __builtin_amdgcn_s_setprio(1); \
;     for (int m = 0; m < 4; ++m) for (int n = 0; n < 2; ++n) for (int k = 0; k < 2; ++k) \
;       acc[ai][bj][m][n] = __builtin_amdgcn_mfma_f32_16x16x32_bf16(At_[m][k], Bt_[n][k], acc[ai][bj][m][n], 0, 0, 0); \
;     __builtin_amdgcn_s_setprio(0); } while (0)
; #define G8_WV(n) asm volatile("s_waitcnt vmcnt(" #n ")" ::: "memory")
; #define G8_WL(n) asm volatile("s_waitcnt lgkmcnt(" #n ")" ::: "memory")
; #define G8_BAR __builtin_amdgcn_s_barrier()
; #define G8_SCHED __builtin_amdgcn_sched_barrier(0)
; DI void gemm8p(const u16* __restrict__ A, const u16* __restrict__ Bt, int brow, int bcol, f32x4 (&acc)[2][2][4][2]) {
;     ...
; #pragma unroll 1
;   for (int t = 0; t < nt - 2; t += 2) {
;     G8_LDB(B0, 0, 0); G8_SCHED; G8_LDA(At, 0, 0); G8_STAGE(G8_SA(1, 1), A, brow + HALF, t + 1);
;     G8_WL(8); G8_BAR; G8_WL(0); G8_MMA(0, 0, At, B0); G8_BAR; G8_SCHED;
;     G8_LDB(B1, 0, 1); G8_STAGE(G8_SB(0, 0), Bt, bcol, t + 2);
;     G8_BAR; G8_WL(0); G8_MMA(0, 1, At, B1); G8_BAR;
;     G8_LDA(At, 0, 1); G8_STAGE(G8_SA(0, 0), A, brow, t + 2);
;     G8_BAR; G8_WL(0); G8_MMA(1, 0, At, B0); G8_BAR; G8_SCHED;
;     G8_STAGE(G8_SB(0, 1), Bt, bcol + HALF, t + 2);
;     G8_WV(6); G8_BAR; G8_MMA(1, 1, At, B1); G8_BAR;
;     G8_LDB(B0, 1, 0); G8_SCHED; G8_LDA(At, 1, 0); G8_STAGE(G8_SA(0, 1), A, brow + HALF, t + 2);
;     G8_WL(8); G8_BAR; G8_WL(0); G8_MMA(0, 0, At, B0); G8_BAR; G8_SCHED;
;     G8_LDB(B1, 1, 1); G8_STAGE(G8_SB(1, 0), Bt, bcol, t + 3);
;     G8_BAR; G8_WL(0); G8_MMA(0, 1, At, B1); G8_BAR;
;     G8_LDA(At, 1, 1); G8_STAGE(G8_SA(1, 0), A, brow, t + 3);
;     G8_BAR; G8_WL(0); G8_MMA(1, 0, At, B0); G8_BAR; G8_SCHED;
;     G8_STAGE(G8_SB(1, 1), Bt, bcol + HALF, t + 3);
;     G8_WV(6); G8_BAR; G8_MMA(1, 1, At, B1); G8_BAR;
.LBB0_85:
	ds_read_b128 v[170:173], v166
	ds_read_b128 v[174:177], v166 offset:1024
	ds_read_b128 v[178:181], v166 offset:2048
	ds_read_b128 v[186:189], v166 offset:3072
	v_add_u32_e32 v167, 0xc000, v151
	v_lshl_add_u64 v[182:183], s[34:35], 0, v[140:141]
	v_readfirstlane_b32 s7, v167
	v_lshl_add_u64 v[168:169], v[182:183], 0, s[98:99]
	s_mov_b32 m0, s7
	ds_read_b128 v[190:193], v148
	ds_read_b128 v[194:197], v148 offset:1024
	ds_read_b128 v[198:201], v147
	ds_read_b128 v[202:205], v147 offset:1024
	ds_read_b128 v[206:209], v146
	ds_read_b128 v[210:213], v146 offset:1024
	ds_read_b128 v[222:225], v145
	ds_read_b128 v[226:229], v145 offset:1024
	global_load_lds_dwordx4 v[168:169], off
	v_add_u32_e32 v168, 0xe000, v151
	v_lshl_add_u64 v[246:247], s[34:35], 0, v[142:143]
	v_readfirstlane_b32 s7, v168
	v_lshl_add_u64 v[230:231], v[246:247], 0, s[98:99]
	s_mov_b32 m0, s7
	s_nop 0
	global_load_lds_dwordx4 v[230:231], off
	s_waitcnt lgkmcnt(8)
	s_barrier
	s_waitcnt lgkmcnt(0)
	s_setprio 1
	s_waitcnt lgkmcnt(0)
	v_mfma_f32_16x16x32_bf16 v[126:129], v[170:173], v[190:193], v[126:129]
	v_mfma_f32_16x16x32_bf16 v[122:125], v[178:181], v[190:193], v[122:125]
	v_mfma_f32_16x16x32_bf16 v[118:121], v[170:173], v[198:201], v[118:121]
	v_mfma_f32_16x16x32_bf16 v[114:117], v[178:181], v[198:201], v[114:117]
	v_mfma_f32_16x16x32_bf16 v[110:113], v[170:173], v[206:209], v[110:113]
	v_mfma_f32_16x16x32_bf16 v[106:109], v[178:181], v[206:209], v[106:109]
	v_mfma_f32_16x16x32_bf16 v[102:105], v[170:173], v[222:225], v[102:105]
	v_mfma_f32_16x16x32_bf16 v[98:101], v[178:181], v[222:225], v[98:101]
	v_mfma_f32_16x16x32_bf16 v[126:129], v[174:177], v[194:197], v[126:129]
	v_mfma_f32_16x16x32_bf16 v[122:125], v[186:189], v[194:197], v[122:125]
	v_mfma_f32_16x16x32_bf16 v[118:121], v[174:177], v[202:205], v[118:121]
	v_mfma_f32_16x16x32_bf16 v[114:117], v[186:189], v[202:205], v[114:117]
	v_mfma_f32_16x16x32_bf16 v[110:113], v[174:177], v[210:213], v[110:113]
	v_mfma_f32_16x16x32_bf16 v[106:109], v[186:189], v[210:213], v[106:109]
	v_mfma_f32_16x16x32_bf16 v[102:105], v[174:177], v[226:229], v[102:105]
	v_mfma_f32_16x16x32_bf16 v[98:101], v[186:189], v[226:229], v[98:101]
	s_setprio 0
	s_barrier
	v_lshl_add_u64 v[248:249], s[34:35], 0, v[136:137]
	v_readfirstlane_b32 s7, v149
	v_lshl_add_u64 v[250:251], v[248:249], 0, s[18:19]
	s_mov_b32 m0, s7
	ds_read_b128 v[230:233], v165
	ds_read_b128 v[234:237], v165 offset:1024
	ds_read_b128 v[238:241], v165 offset:2048
	ds_read_b128 v[242:245], v165 offset:3072
	global_load_lds_dwordx4 v[250:251], off
	v_lshl_add_u64 v[250:251], s[34:35], 0, v[138:139]
	v_readfirstlane_b32 s7, v150
	v_lshl_add_u64 v[252:253], v[250:251], 0, s[18:19]
	s_mov_b32 m0, s7
	s_nop 0
	global_load_lds_dwordx4 v[252:253], off
	s_barrier
	s_waitcnt lgkmcnt(0)
	s_setprio 1
	s_waitcnt lgkmcnt(0)
	v_mfma_f32_16x16x32_bf16 v[94:97], v[230:233], v[190:193], v[94:97]
	v_mfma_f32_16x16x32_bf16 v[90:93], v[238:241], v[190:193], v[90:93]
	v_mfma_f32_16x16x32_bf16 v[86:89], v[230:233], v[198:201], v[86:89]
	v_mfma_f32_16x16x32_bf16 v[82:85], v[238:241], v[198:201], v[82:85]
	v_mfma_f32_16x16x32_bf16 v[78:81], v[230:233], v[206:209], v[78:81]
	v_mfma_f32_16x16x32_bf16 v[74:77], v[238:241], v[206:209], v[74:77]
	v_mfma_f32_16x16x32_bf16 v[70:73], v[230:233], v[222:225], v[70:73]
	v_mfma_f32_16x16x32_bf16 v[66:69], v[238:241], v[222:225], v[66:69]
	v_mfma_f32_16x16x32_bf16 v[94:97], v[234:237], v[194:197], v[94:97]
	v_mfma_f32_16x16x32_bf16 v[90:93], v[242:245], v[194:197], v[90:93]
	v_mfma_f32_16x16x32_bf16 v[86:89], v[234:237], v[202:205], v[86:89]
	v_mfma_f32_16x16x32_bf16 v[82:85], v[242:245], v[202:205], v[82:85]
	v_mfma_f32_16x16x32_bf16 v[78:81], v[234:237], v[210:213], v[78:81]
	v_mfma_f32_16x16x32_bf16 v[74:77], v[242:245], v[210:213], v[74:77]
	v_mfma_f32_16x16x32_bf16 v[70:73], v[234:237], v[226:229], v[70:73]
	v_mfma_f32_16x16x32_bf16 v[66:69], v[242:245], v[226:229], v[66:69]
	s_setprio 0
	v_readfirstlane_b32 s7, v151
	v_lshl_add_u64 v[252:253], v[182:183], 0, s[96:97]
	s_mov_b32 m0, s7
	v_readfirstlane_b32 s7, v153
	s_barrier
	ds_read_b128 v[190:193], v148 offset:16384
	ds_read_b128 v[194:197], v148 offset:17408
	ds_read_b128 v[198:201], v147 offset:16384
	ds_read_b128 v[202:205], v147 offset:17408
	ds_read_b128 v[206:209], v146 offset:16384
	ds_read_b128 v[210:213], v146 offset:17408
	ds_read_b128 v[222:225], v145 offset:16384
	ds_read_b128 v[226:229], v145 offset:17408
	global_load_lds_dwordx4 v[252:253], off
	v_lshl_add_u64 v[252:253], v[246:247], 0, s[96:97]
	s_mov_b32 m0, s7
	s_nop 0
	global_load_lds_dwordx4 v[252:253], off
	s_barrier
	s_waitcnt lgkmcnt(0)
	s_setprio 1
	s_waitcnt lgkmcnt(0)
	v_mfma_f32_16x16x32_bf16 v[62:65], v[170:173], v[190:193], v[62:65]
	v_mfma_f32_16x16x32_bf16 v[58:61], v[178:181], v[190:193], v[58:61]
	v_mfma_f32_16x16x32_bf16 v[54:57], v[170:173], v[198:201], v[54:57]
	v_mfma_f32_16x16x32_bf16 v[50:53], v[178:181], v[198:201], v[50:53]
	v_mfma_f32_16x16x32_bf16 v[46:49], v[170:173], v[206:209], v[46:49]
	v_mfma_f32_16x16x32_bf16 v[42:45], v[178:181], v[206:209], v[42:45]
	v_mfma_f32_16x16x32_bf16 v[38:41], v[170:173], v[222:225], v[38:41]
	v_mfma_f32_16x16x32_bf16 v[34:37], v[178:181], v[222:225], v[34:37]
	v_mfma_f32_16x16x32_bf16 v[62:65], v[174:177], v[194:197], v[62:65]
	v_mfma_f32_16x16x32_bf16 v[58:61], v[186:189], v[194:197], v[58:61]
	v_mfma_f32_16x16x32_bf16 v[54:57], v[174:177], v[202:205], v[54:57]
	v_mfma_f32_16x16x32_bf16 v[50:53], v[186:189], v[202:205], v[50:53]
	v_mfma_f32_16x16x32_bf16 v[46:49], v[174:177], v[210:213], v[46:49]
	v_mfma_f32_16x16x32_bf16 v[42:45], v[186:189], v[210:213], v[42:45]
	v_mfma_f32_16x16x32_bf16 v[38:41], v[174:177], v[226:229], v[38:41]
	v_mfma_f32_16x16x32_bf16 v[34:37], v[186:189], v[226:229], v[34:37]
	s_setprio 0
	s_barrier
; #define G8_LDA(dst, b, h) for (int m = 0; m < 4; ++m) for (int k = 0; k < 2; ++k) \
;     dst[m][k] = *reinterpret_cast<const bf16x8*>((char*)G8_SA(b, h) + g8_lds_byte(wr * 64 + m * 16 + fr, k * 32 + fq * 8))
; #define G8_LDB(dst, b, h) for (int n = 0; n < 2; ++n) for (int k = 0; k < 2; ++k) \
;     dst[n][k] = *reinterpret_cast<const bf16x8*>((char*)G8_SB(b, h) + g8_lds_byte(wc * 32 + n * 16 + fr, k * 32 + fq * 8))
; #define G8_MMA(ai, bj, At_, Bt_) do { __builtin_amdgcn_s_setprio(1); \
;     for (int m = 0; m < 4; ++m) for (int n = 0; n < 2; ++n) for (int k = 0; k < 2; ++k) \
;       acc[ai][bj][m][n] = __builtin_amdgcn_mfma_f32_16x16x32_bf16(At_[m][k], Bt_[n][k], acc[ai][bj][m][n], 0, 0, 0); \
;     __builtin_amdgcn_s_setprio(0); } while (0)
; #define G8_WV(n) asm volatile("s_waitcnt vmcnt(" #n ")" ::: "memory")
; #define G8_WL(n) asm volatile("s_waitcnt lgkmcnt(" #n ")" ::: "memory")
; #define G8_BAR __builtin_amdgcn_s_barrier()
; #define G8_SCHED __builtin_amdgcn_sched_barrier(0)
; DI void gemm8p(const u16* __restrict__ A, const u16* __restrict__ Bt, int brow, int bcol, f32x4 (&acc)[2][2][4][2]) {
;     ...
;     G8_LDB(B0, 0, 0); G8_SCHED; G8_LDA(At, 0, 0); G8_STAGE(G8_SA(1, 1), A, brow + HALF, t + 1);
;     G8_WL(8); G8_BAR; G8_WL(0); G8_MMA(0, 0, At, B0); G8_BAR; G8_SCHED;
;     G8_LDB(B1, 0, 1); G8_STAGE(G8_SB(0, 0), Bt, bcol, t + 2);
;     G8_BAR; G8_WL(0); G8_MMA(0, 1, At, B1); G8_BAR;
;     G8_LDA(At, 0, 1); G8_STAGE(G8_SA(0, 0), A, brow, t + 2);
;     G8_BAR; G8_WL(0); G8_MMA(1, 0, At, B0); G8_BAR; G8_SCHED;
;     G8_STAGE(G8_SB(0, 1), Bt, bcol + HALF, t + 2);
;     G8_WV(6); G8_BAR; G8_MMA(1, 1, At, B1); G8_BAR;
;     G8_LDB(B0, 1, 0); G8_SCHED; G8_LDA(At, 1, 0); G8_STAGE(G8_SA(0, 1), A, brow + HALF, t + 2);
;     G8_WL(8); G8_BAR; G8_WL(0); G8_MMA(0, 0, At, B0); G8_BAR; G8_SCHED;
;     G8_LDB(B1, 1, 1); G8_STAGE(G8_SB(1, 0), Bt, bcol, t + 3);
;     G8_BAR; G8_WL(0); G8_MMA(0, 1, At, B1); G8_BAR;
;     G8_LDA(At, 1, 1); G8_STAGE(G8_SA(1, 0), A, brow, t + 3);
;     G8_BAR; G8_WL(0); G8_MMA(1, 0, At, B0); G8_BAR; G8_SCHED;
;     G8_STAGE(G8_SB(1, 1), Bt, bcol + HALF, t + 3);
;     G8_WV(6); G8_BAR; G8_MMA(1, 1, At, B1); G8_BAR;
	v_readfirstlane_b32 s7, v154
	v_lshl_add_u64 v[170:171], v[248:249], 0, s[90:91]
	s_mov_b32 m0, s7
	v_readfirstlane_b32 s7, v155
	global_load_lds_dwordx4 v[170:171], off
	v_lshl_add_u64 v[170:171], v[250:251], 0, s[90:91]
	s_mov_b32 m0, s7
	s_nop 0
	global_load_lds_dwordx4 v[170:171], off
	s_waitcnt vmcnt(6)
	s_barrier
	s_setprio 1
	v_mfma_f32_16x16x32_bf16 v[30:33], v[230:233], v[190:193], v[30:33]
	v_mfma_f32_16x16x32_bf16 v[26:29], v[238:241], v[190:193], v[26:29]
	v_mfma_f32_16x16x32_bf16 v[22:25], v[230:233], v[198:201], v[22:25]
	v_mfma_f32_16x16x32_bf16 v[18:21], v[238:241], v[198:201], v[18:21]
	v_mfma_f32_16x16x32_bf16 v[14:17], v[230:233], v[206:209], v[14:17]
	v_mfma_f32_16x16x32_bf16 v[10:13], v[238:241], v[206:209], v[10:13]
	v_mfma_f32_16x16x32_bf16 v[6:9], v[230:233], v[222:225], v[6:9]
	v_mfma_f32_16x16x32_bf16 v[0:3], v[238:241], v[222:225], v[0:3]
	v_mfma_f32_16x16x32_bf16 v[30:33], v[234:237], v[194:197], v[30:33]
	v_mfma_f32_16x16x32_bf16 v[26:29], v[242:245], v[194:197], v[26:29]
	v_mfma_f32_16x16x32_bf16 v[22:25], v[234:237], v[202:205], v[22:25]
	v_mfma_f32_16x16x32_bf16 v[18:21], v[242:245], v[202:205], v[18:21]
	v_mfma_f32_16x16x32_bf16 v[14:17], v[234:237], v[210:213], v[14:17]
	v_mfma_f32_16x16x32_bf16 v[10:13], v[242:245], v[210:213], v[10:13]
	v_mfma_f32_16x16x32_bf16 v[6:9], v[234:237], v[226:229], v[6:9]
	v_mfma_f32_16x16x32_bf16 v[0:3], v[242:245], v[226:229], v[0:3]
	s_setprio 0
	s_barrier
	ds_read_b128 v[170:173], v156
	ds_read_b128 v[174:177], v156 offset:1024
	ds_read_b128 v[178:181], v156 offset:2048
	ds_read_b128 v[186:189], v156 offset:3072
	v_readfirstlane_b32 s7, v157
	v_lshl_add_u64 v[230:231], v[182:183], 0, s[56:57]
	s_mov_b32 m0, s7
	v_readfirstlane_b32 s7, v158
	ds_read_b128 v[190:193], v148 offset:32768
	ds_read_b128 v[194:197], v148 offset:33792
	ds_read_b128 v[198:201], v147 offset:32768
	ds_read_b128 v[202:205], v147 offset:33792
	ds_read_b128 v[206:209], v146 offset:32768
	ds_read_b128 v[210:213], v146 offset:33792
	ds_read_b128 v[222:225], v145 offset:32768
	ds_read_b128 v[226:229], v145 offset:33792
	global_load_lds_dwordx4 v[230:231], off
	v_lshl_add_u64 v[230:231], v[246:247], 0, s[56:57]
	s_mov_b32 m0, s7
	s_nop 0
	global_load_lds_dwordx4 v[230:231], off
	s_waitcnt lgkmcnt(8)
	s_barrier
	s_waitcnt lgkmcnt(0)
	s_setprio 1
	s_waitcnt lgkmcnt(0)
	v_mfma_f32_16x16x32_bf16 v[126:129], v[170:173], v[190:193], v[126:129]
	v_mfma_f32_16x16x32_bf16 v[122:125], v[178:181], v[190:193], v[122:125]
	v_mfma_f32_16x16x32_bf16 v[118:121], v[170:173], v[198:201], v[118:121]
	v_mfma_f32_16x16x32_bf16 v[114:117], v[178:181], v[198:201], v[114:117]
	v_mfma_f32_16x16x32_bf16 v[110:113], v[170:173], v[206:209], v[110:113]
	v_mfma_f32_16x16x32_bf16 v[106:109], v[178:181], v[206:209], v[106:109]
	v_mfma_f32_16x16x32_bf16 v[102:105], v[170:173], v[222:225], v[102:105]
	v_mfma_f32_16x16x32_bf16 v[98:101], v[178:181], v[222:225], v[98:101]
	v_mfma_f32_16x16x32_bf16 v[126:129], v[174:177], v[194:197], v[126:129]
	v_mfma_f32_16x16x32_bf16 v[122:125], v[186:189], v[194:197], v[122:125]
	v_mfma_f32_16x16x32_bf16 v[118:121], v[174:177], v[202:205], v[118:121]
	v_mfma_f32_16x16x32_bf16 v[114:117], v[186:189], v[202:205], v[114:117]
	v_mfma_f32_16x16x32_bf16 v[110:113], v[174:177], v[210:213], v[110:113]
	v_mfma_f32_16x16x32_bf16 v[106:109], v[186:189], v[210:213], v[106:109]
	v_mfma_f32_16x16x32_bf16 v[102:105], v[174:177], v[226:229], v[102:105]
	v_mfma_f32_16x16x32_bf16 v[98:101], v[186:189], v[226:229], v[98:101]
	s_setprio 0
	s_barrier
	v_readfirstlane_b32 s7, v159
	v_lshl_add_u64 v[252:253], v[248:249], 0, s[70:71]
	s_mov_b32 m0, s7
	v_readfirstlane_b32 s7, v160
	ds_read_b128 v[230:233], v152
	ds_read_b128 v[234:237], v152 offset:1024
	ds_read_b128 v[238:241], v152 offset:2048
	ds_read_b128 v[242:245], v152 offset:3072
	global_load_lds_dwordx4 v[252:253], off
	v_lshl_add_u64 v[252:253], v[250:251], 0, s[70:71]
	s_mov_b32 m0, s7
	s_nop 0
	global_load_lds_dwordx4 v[252:253], off
	s_barrier
	s_waitcnt lgkmcnt(0)
	s_setprio 1
	s_waitcnt lgkmcnt(0)
	v_mfma_f32_16x16x32_bf16 v[94:97], v[230:233], v[190:193], v[94:97]
	v_mfma_f32_16x16x32_bf16 v[90:93], v[238:241], v[190:193], v[90:93]
	v_mfma_f32_16x16x32_bf16 v[86:89], v[230:233], v[198:201], v[86:89]
	v_mfma_f32_16x16x32_bf16 v[82:85], v[238:241], v[198:201], v[82:85]
	v_mfma_f32_16x16x32_bf16 v[78:81], v[230:233], v[206:209], v[78:81]
	v_mfma_f32_16x16x32_bf16 v[74:77], v[238:241], v[206:209], v[74:77]
	v_mfma_f32_16x16x32_bf16 v[70:73], v[230:233], v[222:225], v[70:73]
	v_mfma_f32_16x16x32_bf16 v[66:69], v[238:241], v[222:225], v[66:69]
	v_mfma_f32_16x16x32_bf16 v[94:97], v[234:237], v[194:197], v[94:97]
	v_mfma_f32_16x16x32_bf16 v[90:93], v[242:245], v[194:197], v[90:93]
	v_mfma_f32_16x16x32_bf16 v[86:89], v[234:237], v[202:205], v[86:89]
	v_mfma_f32_16x16x32_bf16 v[82:85], v[242:245], v[202:205], v[82:85]
	v_mfma_f32_16x16x32_bf16 v[78:81], v[234:237], v[210:213], v[78:81]
	v_mfma_f32_16x16x32_bf16 v[74:77], v[242:245], v[210:213], v[74:77]
	v_mfma_f32_16x16x32_bf16 v[70:73], v[234:237], v[226:229], v[70:73]
	v_mfma_f32_16x16x32_bf16 v[66:69], v[242:245], v[226:229], v[66:69]
	s_setprio 0
	v_readfirstlane_b32 s7, v161
	v_lshl_add_u64 v[182:183], v[182:183], 0, s[88:89]
	s_mov_b32 m0, s7
	v_readfirstlane_b32 s7, v162
	s_barrier
	ds_read_b128 v[190:193], v148 offset:49152
	ds_read_b128 v[194:197], v148 offset:50176
	ds_read_b128 v[198:201], v147 offset:49152
	ds_read_b128 v[202:205], v147 offset:50176
	ds_read_b128 v[206:209], v146 offset:49152
	ds_read_b128 v[210:213], v146 offset:50176
	ds_read_b128 v[222:225], v145 offset:49152
	ds_read_b128 v[226:229], v145 offset:50176
	global_load_lds_dwordx4 v[182:183], off
	v_lshl_add_u64 v[182:183], v[246:247], 0, s[88:89]
	s_mov_b32 m0, s7
	s_nop 0
	global_load_lds_dwordx4 v[182:183], off
	s_barrier
; #define G8_LDA(dst, b, h) for (int m = 0; m < 4; ++m) for (int k = 0; k < 2; ++k) \
;     dst[m][k] = *reinterpret_cast<const bf16x8*>((char*)G8_SA(b, h) + g8_lds_byte(wr * 64 + m * 16 + fr, k * 32 + fq * 8))
; #define G8_LDB(dst, b, h) for (int n = 0; n < 2; ++n) for (int k = 0; k < 2; ++k) \
;     dst[n][k] = *reinterpret_cast<const bf16x8*>((char*)G8_SB(b, h) + g8_lds_byte(wc * 32 + n * 16 + fr, k * 32 + fq * 8))
; #define G8_MMA(ai, bj, At_, Bt_) do { __builtin_amdgcn_s_setprio(1); \
;     for (int m = 0; m < 4; ++m) for (int n = 0; n < 2; ++n) for (int k = 0; k < 2; ++k) \
;       acc[ai][bj][m][n] = __builtin_amdgcn_mfma_f32_16x16x32_bf16(At_[m][k], Bt_[n][k], acc[ai][bj][m][n], 0, 0, 0); \
;     __builtin_amdgcn_s_setprio(0); } while (0)
; #define G8_WV(n) asm volatile("s_waitcnt vmcnt(" #n ")" ::: "memory")
; #define G8_WL(n) asm volatile("s_waitcnt lgkmcnt(" #n ")" ::: "memory")
; #define G8_BAR __builtin_amdgcn_s_barrier()
; #define G8_SCHED __builtin_amdgcn_sched_barrier(0)
; DI void gemm8p(const u16* __restrict__ A, const u16* __restrict__ Bt, int brow, int bcol, f32x4 (&acc)[2][2][4][2]) {
;     ...
;     G8_WL(8); G8_BAR; G8_WL(0); G8_MMA(0, 0, At, B0); G8_BAR; G8_SCHED;
;     G8_LDB(B1, 1, 1); G8_STAGE(G8_SB(1, 0), Bt, bcol, t + 3);
;     G8_BAR; G8_WL(0); G8_MMA(0, 1, At, B1); G8_BAR;
;     G8_LDA(At, 1, 1); G8_STAGE(G8_SA(1, 0), A, brow, t + 3);
;     G8_BAR; G8_WL(0); G8_MMA(1, 0, At, B0); G8_BAR; G8_SCHED;
;     G8_STAGE(G8_SB(1, 1), Bt, bcol + HALF, t + 3);
;     G8_WV(6); G8_BAR; G8_MMA(1, 1, At, B1); G8_BAR;
;   }
;   { G8_LDB(B0, 0, 0); G8_LDA(At, 0, 0); G8_STAGE(G8_SA(1, 1), A, brow + HALF, nt - 1);
;     G8_BAR; G8_WL(0); G8_MMA(0, 0, At, B0); G8_BAR;
;     G8_LDB(B1, 0, 1); G8_BAR; G8_WL(0); G8_MMA(0, 1, At, B1); G8_BAR;
	s_waitcnt lgkmcnt(0)
	s_setprio 1
	s_waitcnt lgkmcnt(0)
	v_mfma_f32_16x16x32_bf16 v[62:65], v[170:173], v[190:193], v[62:65]
	v_mfma_f32_16x16x32_bf16 v[58:61], v[178:181], v[190:193], v[58:61]
	v_mfma_f32_16x16x32_bf16 v[54:57], v[170:173], v[198:201], v[54:57]
	v_mfma_f32_16x16x32_bf16 v[50:53], v[178:181], v[198:201], v[50:53]
	v_mfma_f32_16x16x32_bf16 v[46:49], v[170:173], v[206:209], v[46:49]
	v_mfma_f32_16x16x32_bf16 v[42:45], v[178:181], v[206:209], v[42:45]
	v_mfma_f32_16x16x32_bf16 v[38:41], v[170:173], v[222:225], v[38:41]
	v_mfma_f32_16x16x32_bf16 v[34:37], v[178:181], v[222:225], v[34:37]
	v_mfma_f32_16x16x32_bf16 v[62:65], v[174:177], v[194:197], v[62:65]
	v_mfma_f32_16x16x32_bf16 v[58:61], v[186:189], v[194:197], v[58:61]
	v_mfma_f32_16x16x32_bf16 v[54:57], v[174:177], v[202:205], v[54:57]
	v_mfma_f32_16x16x32_bf16 v[50:53], v[186:189], v[202:205], v[50:53]
	v_mfma_f32_16x16x32_bf16 v[46:49], v[174:177], v[210:213], v[46:49]
	v_mfma_f32_16x16x32_bf16 v[42:45], v[186:189], v[210:213], v[42:45]
	v_mfma_f32_16x16x32_bf16 v[38:41], v[174:177], v[226:229], v[38:41]
	v_mfma_f32_16x16x32_bf16 v[34:37], v[186:189], v[226:229], v[34:37]
	s_setprio 0
	s_barrier
	v_readfirstlane_b32 s7, v163
	v_lshl_add_u64 v[170:171], v[248:249], 0, s[40:41]
	s_mov_b32 m0, s7
	v_readfirstlane_b32 s7, v164
	global_load_lds_dwordx4 v[170:171], off
	v_lshl_add_u64 v[170:171], v[250:251], 0, s[40:41]
	s_mov_b32 m0, s7
	s_nop 0
	global_load_lds_dwordx4 v[170:171], off
	s_waitcnt vmcnt(6)
	s_barrier
	s_setprio 1
	v_mfma_f32_16x16x32_bf16 v[30:33], v[230:233], v[190:193], v[30:33]
	v_mfma_f32_16x16x32_bf16 v[26:29], v[238:241], v[190:193], v[26:29]
	v_mfma_f32_16x16x32_bf16 v[22:25], v[230:233], v[198:201], v[22:25]
	v_mfma_f32_16x16x32_bf16 v[18:21], v[238:241], v[198:201], v[18:21]
	v_mfma_f32_16x16x32_bf16 v[14:17], v[230:233], v[206:209], v[14:17]
	v_mfma_f32_16x16x32_bf16 v[10:13], v[238:241], v[206:209], v[10:13]
	v_mfma_f32_16x16x32_bf16 v[6:9], v[230:233], v[222:225], v[6:9]
	v_mfma_f32_16x16x32_bf16 v[0:3], v[238:241], v[222:225], v[0:3]
	v_mfma_f32_16x16x32_bf16 v[30:33], v[234:237], v[194:197], v[30:33]
	v_mfma_f32_16x16x32_bf16 v[26:29], v[242:245], v[194:197], v[26:29]
	v_mfma_f32_16x16x32_bf16 v[22:25], v[234:237], v[202:205], v[22:25]
	v_mfma_f32_16x16x32_bf16 v[18:21], v[242:245], v[202:205], v[18:21]
	v_mfma_f32_16x16x32_bf16 v[14:17], v[234:237], v[210:213], v[14:17]
	v_mfma_f32_16x16x32_bf16 v[10:13], v[242:245], v[210:213], v[10:13]
	v_mfma_f32_16x16x32_bf16 v[6:9], v[234:237], v[226:229], v[6:9]
	v_mfma_f32_16x16x32_bf16 v[0:3], v[242:245], v[226:229], v[0:3]
	s_setprio 0
	s_add_i32 s5, s5, 2
	v_lshl_add_u64 v[136:137], v[136:137], 0, s[18:19]
	v_lshl_add_u64 v[138:139], v[138:139], 0, s[18:19]
	v_lshl_add_u64 v[140:141], v[140:141], 0, s[18:19]
	s_cmp_lt_u32 s5, 12
	v_lshl_add_u64 v[142:143], v[142:143], 0, s[18:19]
	s_barrier
	s_cbranch_scc1 .LBB0_85
	s_mov_b64 s[8:9], 0x780
	v_readfirstlane_b32 s5, v167
	v_lshl_add_u64 v[132:133], v[132:133], 0, s[8:9]
	s_mov_b32 m0, s5
	v_readfirstlane_b32 s5, v168
	ds_read_b128 v[136:139], v166
	ds_read_b128 v[140:143], v166 offset:1024
	ds_read_b128 v[158:161], v166 offset:2048
	ds_read_b128 v[170:173], v166 offset:3072
	ds_read_b128 v[174:177], v148
	ds_read_b128 v[178:181], v148 offset:1024
	ds_read_b128 v[186:189], v147
	ds_read_b128 v[190:193], v147 offset:1024
	ds_read_b128 v[194:197], v146
	ds_read_b128 v[198:201], v146 offset:1024
	ds_read_b128 v[202:205], v145
	ds_read_b128 v[206:209], v145 offset:1024
	global_load_lds_dwordx4 v[132:133], off
	v_lshl_add_u64 v[132:133], v[134:135], 0, s[8:9]
	s_mov_b32 m0, s5
	s_nop 0
	global_load_lds_dwordx4 v[132:133], off
	s_barrier
	s_waitcnt lgkmcnt(0)
	s_setprio 1
	s_waitcnt lgkmcnt(0)
	v_mfma_f32_16x16x32_bf16 v[126:129], v[136:139], v[174:177], v[126:129]
	v_mfma_f32_16x16x32_bf16 v[122:125], v[158:161], v[174:177], v[122:125]
	v_mfma_f32_16x16x32_bf16 v[118:121], v[136:139], v[186:189], v[118:121]
	v_mfma_f32_16x16x32_bf16 v[114:117], v[158:161], v[186:189], v[114:117]
	v_mfma_f32_16x16x32_bf16 v[110:113], v[136:139], v[194:197], v[110:113]
	v_mfma_f32_16x16x32_bf16 v[106:109], v[158:161], v[194:197], v[106:109]
	v_mfma_f32_16x16x32_bf16 v[102:105], v[136:139], v[202:205], v[102:105]
	v_mfma_f32_16x16x32_bf16 v[98:101], v[158:161], v[202:205], v[98:101]
	v_mfma_f32_16x16x32_bf16 v[126:129], v[140:143], v[178:181], v[126:129]
	v_mfma_f32_16x16x32_bf16 v[122:125], v[170:173], v[178:181], v[122:125]
	v_mfma_f32_16x16x32_bf16 v[118:121], v[140:143], v[190:193], v[118:121]
	v_mfma_f32_16x16x32_bf16 v[114:117], v[170:173], v[190:193], v[114:117]
	v_mfma_f32_16x16x32_bf16 v[110:113], v[140:143], v[198:201], v[110:113]
	v_mfma_f32_16x16x32_bf16 v[106:109], v[170:173], v[198:201], v[106:109]
	v_mfma_f32_16x16x32_bf16 v[102:105], v[140:143], v[206:209], v[102:105]
	v_mfma_f32_16x16x32_bf16 v[98:101], v[170:173], v[206:209], v[98:101]
	s_setprio 0
	s_barrier
	ds_read_b128 v[132:135], v165
	ds_read_b128 v[166:169], v165 offset:1024
	ds_read_b128 v[210:213], v165 offset:2048
	ds_read_b128 v[162:165], v165 offset:3072
	s_barrier
; #define G8_LDA(dst, b, h) for (int m = 0; m < 4; ++m) for (int k = 0; k < 2; ++k) \
;     dst[m][k] = *reinterpret_cast<const bf16x8*>((char*)G8_SA(b, h) + g8_lds_byte(wr * 64 + m * 16 + fr, k * 32 + fq * 8))
; #define G8_LDB(dst, b, h) for (int n = 0; n < 2; ++n) for (int k = 0; k < 2; ++k) \
;     dst[n][k] = *reinterpret_cast<const bf16x8*>((char*)G8_SB(b, h) + g8_lds_byte(wc * 32 + n * 16 + fr, k * 32 + fq * 8))
; #define G8_MMA(ai, bj, At_, Bt_) do { __builtin_amdgcn_s_setprio(1); \
;     for (int m = 0; m < 4; ++m) for (int n = 0; n < 2; ++n) for (int k = 0; k < 2; ++k) \
;       acc[ai][bj][m][n] = __builtin_amdgcn_mfma_f32_16x16x32_bf16(At_[m][k], Bt_[n][k], acc[ai][bj][m][n], 0, 0, 0); \
;     __builtin_amdgcn_s_setprio(0); } while (0)
; #define G8_WV(n) asm volatile("s_waitcnt vmcnt(" #n ")" ::: "memory")
; #define G8_WL(n) asm volatile("s_waitcnt lgkmcnt(" #n ")" ::: "memory")
; #define G8_BAR __builtin_amdgcn_s_barrier()
; DI void gemm8p(const u16* __restrict__ A, const u16* __restrict__ Bt, int brow, int bcol, f32x4 (&acc)[2][2][4][2]) {
;     ...
;     G8_LDB(B1, 0, 1); G8_BAR; G8_WL(0); G8_MMA(0, 1, At, B1); G8_BAR;
;     G8_LDA(At, 0, 1); G8_WV(4); G8_BAR; G8_WL(0); G8_MMA(1, 0, At, B0); G8_MMA(1, 1, At, B1); G8_BAR; }
;   { G8_LDB(B0, 1, 0); G8_LDA(At, 1, 0); G8_WV(2); G8_BAR; G8_WL(0); G8_MMA(0, 0, At, B0); G8_BAR;
;     G8_LDB(B1, 1, 1); G8_WV(0); G8_BAR; G8_WL(0); G8_MMA(0, 1, At, B1); G8_BAR;
	s_waitcnt lgkmcnt(0)
	s_setprio 1
	s_waitcnt lgkmcnt(0)
	v_mfma_f32_16x16x32_bf16 v[78:81], v[132:135], v[194:197], v[78:81]
	v_mfma_f32_16x16x32_bf16 v[74:77], v[210:213], v[194:197], v[74:77]
	v_mfma_f32_16x16x32_bf16 v[70:73], v[132:135], v[202:205], v[70:73]
	v_mfma_f32_16x16x32_bf16 v[66:69], v[210:213], v[202:205], v[66:69]
	v_mfma_f32_16x16x32_bf16 v[94:97], v[132:135], v[174:177], v[94:97]
	v_mfma_f32_16x16x32_bf16 v[90:93], v[210:213], v[174:177], v[90:93]
	v_mfma_f32_16x16x32_bf16 v[86:89], v[132:135], v[186:189], v[86:89]
	v_mfma_f32_16x16x32_bf16 v[82:85], v[210:213], v[186:189], v[82:85]
	v_mfma_f32_16x16x32_bf16 v[78:81], v[166:169], v[198:201], v[78:81]
	v_mfma_f32_16x16x32_bf16 v[74:77], v[162:165], v[198:201], v[74:77]
	v_mfma_f32_16x16x32_bf16 v[70:73], v[166:169], v[206:209], v[70:73]
	v_mfma_f32_16x16x32_bf16 v[66:69], v[162:165], v[206:209], v[66:69]
	v_mfma_f32_16x16x32_bf16 v[222:225], v[166:169], v[178:181], v[94:97]
	v_mfma_f32_16x16x32_bf16 v[174:177], v[162:165], v[178:181], v[90:93]
	v_mfma_f32_16x16x32_bf16 v[178:181], v[166:169], v[190:193], v[86:89]
	v_mfma_f32_16x16x32_bf16 v[186:189], v[162:165], v[190:193], v[82:85]
	s_setprio 0
	s_barrier
	s_nop 0
	ds_read_b128 v[82:85], v148 offset:16384
	ds_read_b128 v[86:89], v148 offset:17408
	ds_read_b128 v[90:93], v147 offset:16384
	ds_read_b128 v[94:97], v147 offset:17408
	ds_read_b128 v[190:193], v146 offset:16384
	ds_read_b128 v[194:197], v146 offset:17408
	ds_read_b128 v[198:201], v145 offset:16384
	ds_read_b128 v[202:205], v145 offset:17408
	s_waitcnt vmcnt(4)
	s_barrier
	s_waitcnt lgkmcnt(0)
	s_setprio 1
	s_waitcnt lgkmcnt(0)
	v_mfma_f32_16x16x32_bf16 v[46:49], v[136:139], v[190:193], v[46:49]
	v_mfma_f32_16x16x32_bf16 v[42:45], v[158:161], v[190:193], v[42:45]
	v_mfma_f32_16x16x32_bf16 v[38:41], v[136:139], v[198:201], v[38:41]
	v_mfma_f32_16x16x32_bf16 v[34:37], v[158:161], v[198:201], v[34:37]
	v_mfma_f32_16x16x32_bf16 v[62:65], v[136:139], v[82:85], v[62:65]
	v_mfma_f32_16x16x32_bf16 v[58:61], v[158:161], v[82:85], v[58:61]
	v_mfma_f32_16x16x32_bf16 v[54:57], v[136:139], v[90:93], v[54:57]
	v_mfma_f32_16x16x32_bf16 v[50:53], v[158:161], v[90:93], v[50:53]
	v_mfma_f32_16x16x32_bf16 v[46:49], v[140:143], v[194:197], v[46:49]
	v_mfma_f32_16x16x32_bf16 v[42:45], v[170:173], v[194:197], v[42:45]
	v_mfma_f32_16x16x32_bf16 v[38:41], v[140:143], v[202:205], v[38:41]
	v_mfma_f32_16x16x32_bf16 v[34:37], v[170:173], v[202:205], v[34:37]
	v_mfma_f32_16x16x32_bf16 v[206:209], v[140:143], v[86:89], v[62:65]
	v_mfma_f32_16x16x32_bf16 v[226:229], v[170:173], v[86:89], v[58:61]
	v_mfma_f32_16x16x32_bf16 v[230:233], v[140:143], v[94:97], v[54:57]
	v_mfma_f32_16x16x32_bf16 v[234:237], v[170:173], v[94:97], v[50:53]
	s_setprio 0
	s_setprio 1
	v_mfma_f32_16x16x32_bf16 v[0:3], v[210:213], v[198:201], v[0:3]
	v_mfma_f32_16x16x32_bf16 v[30:33], v[132:135], v[82:85], v[30:33]
	v_mfma_f32_16x16x32_bf16 v[26:29], v[210:213], v[82:85], v[26:29]
	v_mfma_f32_16x16x32_bf16 v[22:25], v[132:135], v[90:93], v[22:25]
	v_mfma_f32_16x16x32_bf16 v[18:21], v[210:213], v[90:93], v[18:21]
	v_mfma_f32_16x16x32_bf16 v[14:17], v[132:135], v[190:193], v[14:17]
	v_mfma_f32_16x16x32_bf16 v[10:13], v[210:213], v[190:193], v[10:13]
	v_mfma_f32_16x16x32_bf16 v[6:9], v[132:135], v[198:201], v[6:9]
	v_mfma_f32_16x16x32_bf16 v[0:3], v[162:165], v[202:205], v[0:3]
	v_mfma_f32_16x16x32_bf16 v[136:139], v[166:169], v[86:89], v[30:33]
	v_mfma_f32_16x16x32_bf16 v[140:143], v[162:165], v[86:89], v[26:29]
	v_mfma_f32_16x16x32_bf16 v[158:161], v[166:169], v[94:97], v[22:25]
	v_mfma_f32_16x16x32_bf16 v[170:173], v[162:165], v[94:97], v[18:21]
	v_mfma_f32_16x16x32_bf16 v[238:241], v[166:169], v[194:197], v[14:17]
	v_mfma_f32_16x16x32_bf16 v[190:193], v[162:165], v[194:197], v[10:13]
	v_mfma_f32_16x16x32_bf16 v[132:135], v[166:169], v[202:205], v[6:9]
	s_setprio 0
	s_barrier
	s_nop 0
	ds_read_b128 v[6:9], v156
	ds_read_b128 v[10:13], v156 offset:1024
	ds_read_b128 v[14:17], v156 offset:2048
	ds_read_b128 v[154:157], v156 offset:3072
	ds_read_b128 v[18:21], v148 offset:32768
	ds_read_b128 v[22:25], v148 offset:33792
	ds_read_b128 v[26:29], v147 offset:32768
	ds_read_b128 v[50:53], v147 offset:33792
	ds_read_b128 v[162:165], v146 offset:32768
	ds_read_b128 v[166:169], v146 offset:33792
	ds_read_b128 v[194:197], v145 offset:32768
	ds_read_b128 v[198:201], v145 offset:33792
	s_waitcnt vmcnt(2)
	s_barrier
; #define G8_LDA(dst, b, h) for (int m = 0; m < 4; ++m) for (int k = 0; k < 2; ++k) \
;     dst[m][k] = *reinterpret_cast<const bf16x8*>((char*)G8_SA(b, h) + g8_lds_byte(wr * 64 + m * 16 + fr, k * 32 + fq * 8))
; #define G8_LDB(dst, b, h) for (int n = 0; n < 2; ++n) for (int k = 0; k < 2; ++k) \
;     dst[n][k] = *reinterpret_cast<const bf16x8*>((char*)G8_SB(b, h) + g8_lds_byte(wc * 32 + n * 16 + fr, k * 32 + fq * 8))
; #define G8_MMA(ai, bj, At_, Bt_) do { __builtin_amdgcn_s_setprio(1); \
;     for (int m = 0; m < 4; ++m) for (int n = 0; n < 2; ++n) for (int k = 0; k < 2; ++k) \
;       acc[ai][bj][m][n] = __builtin_amdgcn_mfma_f32_16x16x32_bf16(At_[m][k], Bt_[n][k], acc[ai][bj][m][n], 0, 0, 0); \
;     __builtin_amdgcn_s_setprio(0); } while (0)
; #define G8_WV(n) asm volatile("s_waitcnt vmcnt(" #n ")" ::: "memory")
; #define G8_WL(n) asm volatile("s_waitcnt lgkmcnt(" #n ")" ::: "memory")
; #define G8_BAR __builtin_amdgcn_s_barrier()
; DI void gemm8p(const u16* __restrict__ A, const u16* __restrict__ Bt, int brow, int bcol, f32x4 (&acc)[2][2][4][2]) {
;     ...
;   { G8_LDB(B0, 1, 0); G8_LDA(At, 1, 0); G8_WV(2); G8_BAR; G8_WL(0); G8_MMA(0, 0, At, B0); G8_BAR;
;     G8_LDB(B1, 1, 1); G8_WV(0); G8_BAR; G8_WL(0); G8_MMA(0, 1, At, B1); G8_BAR;
;     G8_LDA(At, 1, 1); G8_BAR; G8_WL(0); G8_MMA(1, 0, At, B0); G8_MMA(1, 1, At, B1); G8_BAR; }
;   if (wr == 0) G8_BAR;
	s_waitcnt lgkmcnt(0)
	s_setprio 1
	s_waitcnt lgkmcnt(0)
	v_mfma_f32_16x16x32_bf16 v[30:33], v[6:9], v[18:21], v[126:129]
	v_mfma_f32_16x16x32_bf16 v[126:129], v[10:13], v[22:25], v[30:33]
	v_mfma_f32_16x16x32_bf16 v[30:33], v[14:17], v[18:21], v[122:125]
	v_mfma_f32_16x16x32_bf16 v[94:97], v[154:157], v[22:25], v[30:33]
	v_mfma_f32_16x16x32_bf16 v[30:33], v[6:9], v[26:29], v[118:121]
	v_mfma_f32_16x16x32_bf16 v[122:125], v[10:13], v[50:53], v[30:33]
	v_mfma_f32_16x16x32_bf16 v[30:33], v[14:17], v[26:29], v[114:117]
	v_mfma_f32_16x16x32_bf16 v[90:93], v[154:157], v[50:53], v[30:33]
	v_mfma_f32_16x16x32_bf16 v[30:33], v[6:9], v[162:165], v[110:113]
	v_mfma_f32_16x16x32_bf16 v[118:121], v[10:13], v[166:169], v[30:33]
	v_mfma_f32_16x16x32_bf16 v[30:33], v[14:17], v[162:165], v[106:109]
	v_mfma_f32_16x16x32_bf16 v[86:89], v[154:157], v[166:169], v[30:33]
	v_mfma_f32_16x16x32_bf16 v[30:33], v[6:9], v[194:197], v[102:105]
	v_mfma_f32_16x16x32_bf16 v[114:117], v[10:13], v[198:201], v[30:33]
	v_mfma_f32_16x16x32_bf16 v[30:33], v[14:17], v[194:197], v[98:101]
	v_mfma_f32_16x16x32_bf16 v[82:85], v[154:157], v[198:201], v[30:33]
	s_setprio 0
	s_barrier
	ds_read_b128 v[202:205], v152
	ds_read_b128 v[210:213], v152 offset:1024
	ds_read_b128 v[242:245], v152 offset:2048
	ds_read_b128 v[150:153], v152 offset:3072
	s_waitcnt vmcnt(0)
	s_barrier
	s_waitcnt lgkmcnt(0)
	s_setprio 1
	s_waitcnt lgkmcnt(0)
	v_mfma_f32_16x16x32_bf16 v[30:33], v[202:205], v[18:21], v[222:225]
	v_mfma_f32_16x16x32_bf16 v[18:21], v[242:245], v[18:21], v[174:177]
	v_mfma_f32_16x16x32_bf16 v[62:65], v[210:213], v[22:25], v[30:33]
	v_mfma_f32_16x16x32_bf16 v[30:33], v[150:153], v[22:25], v[18:21]
	v_mfma_f32_16x16x32_bf16 v[18:21], v[202:205], v[26:29], v[178:181]
	v_mfma_f32_16x16x32_bf16 v[58:61], v[210:213], v[50:53], v[18:21]
	v_mfma_f32_16x16x32_bf16 v[18:21], v[242:245], v[26:29], v[186:189]
	v_mfma_f32_16x16x32_bf16 v[26:29], v[150:153], v[50:53], v[18:21]
	v_mfma_f32_16x16x32_bf16 v[18:21], v[202:205], v[162:165], v[78:81]
	v_mfma_f32_16x16x32_bf16 v[54:57], v[210:213], v[166:169], v[18:21]
	v_mfma_f32_16x16x32_bf16 v[18:21], v[242:245], v[162:165], v[74:77]
	v_mfma_f32_16x16x32_bf16 v[22:25], v[150:153], v[166:169], v[18:21]
	v_mfma_f32_16x16x32_bf16 v[18:21], v[202:205], v[194:197], v[70:73]
	v_mfma_f32_16x16x32_bf16 v[50:53], v[210:213], v[198:201], v[18:21]
	v_mfma_f32_16x16x32_bf16 v[18:21], v[242:245], v[194:197], v[66:69]
	v_mfma_f32_16x16x32_bf16 v[18:21], v[150:153], v[198:201], v[18:21]
	s_setprio 0
	s_barrier
	ds_read_b128 v[162:165], v148 offset:49152
	ds_read_b128 v[166:169], v148 offset:50176
	ds_read_b128 v[174:177], v147 offset:49152
	ds_read_b128 v[178:181], v147 offset:50176
	ds_read_b128 v[186:189], v146 offset:49152
	ds_read_b128 v[146:149], v146 offset:50176
	ds_read_b128 v[194:197], v145 offset:49152
	ds_read_b128 v[198:201], v145 offset:50176
	s_barrier
	s_waitcnt lgkmcnt(0)
	s_setprio 1
	s_waitcnt lgkmcnt(0)
	v_mfma_f32_16x16x32_bf16 v[66:69], v[6:9], v[162:165], v[206:209]
	v_mfma_f32_16x16x32_bf16 v[110:113], v[10:13], v[166:169], v[66:69]
	v_mfma_f32_16x16x32_bf16 v[66:69], v[14:17], v[162:165], v[226:229]
	v_mfma_f32_16x16x32_bf16 v[78:81], v[154:157], v[166:169], v[66:69]
	v_mfma_f32_16x16x32_bf16 v[66:69], v[6:9], v[174:177], v[230:233]
	v_mfma_f32_16x16x32_bf16 v[46:49], v[6:9], v[186:189], v[46:49]
	v_mfma_f32_16x16x32_bf16 v[6:9], v[6:9], v[194:197], v[38:41]
	v_mfma_f32_16x16x32_bf16 v[106:109], v[10:13], v[178:181], v[66:69]
	v_mfma_f32_16x16x32_bf16 v[66:69], v[14:17], v[174:177], v[234:237]
	v_mfma_f32_16x16x32_bf16 v[42:45], v[14:17], v[186:189], v[42:45]
	v_mfma_f32_16x16x32_bf16 v[98:101], v[10:13], v[198:201], v[6:9]
	v_mfma_f32_16x16x32_bf16 v[6:9], v[14:17], v[194:197], v[34:37]
	v_mfma_f32_16x16x32_bf16 v[74:77], v[154:157], v[178:181], v[66:69]
	v_mfma_f32_16x16x32_bf16 v[102:105], v[10:13], v[146:149], v[46:49]
	v_mfma_f32_16x16x32_bf16 v[70:73], v[154:157], v[146:149], v[42:45]
	v_mfma_f32_16x16x32_bf16 v[66:69], v[154:157], v[198:201], v[6:9]
	s_setprio 0
	s_setprio 1
	v_mfma_f32_16x16x32_bf16 v[6:9], v[202:205], v[162:165], v[136:139]
	v_mfma_f32_16x16x32_bf16 v[46:49], v[210:213], v[166:169], v[6:9]
	v_mfma_f32_16x16x32_bf16 v[6:9], v[242:245], v[162:165], v[140:143]
	v_mfma_f32_16x16x32_bf16 v[14:17], v[150:153], v[166:169], v[6:9]
	v_mfma_f32_16x16x32_bf16 v[6:9], v[202:205], v[174:177], v[158:161]
	v_mfma_f32_16x16x32_bf16 v[42:45], v[210:213], v[178:181], v[6:9]
	v_mfma_f32_16x16x32_bf16 v[6:9], v[242:245], v[174:177], v[170:173]
	v_mfma_f32_16x16x32_bf16 v[10:13], v[150:153], v[178:181], v[6:9]
	v_mfma_f32_16x16x32_bf16 v[6:9], v[202:205], v[186:189], v[238:241]
	v_mfma_f32_16x16x32_bf16 v[38:41], v[210:213], v[146:149], v[6:9]
	v_mfma_f32_16x16x32_bf16 v[6:9], v[242:245], v[186:189], v[190:193]
	v_mfma_f32_16x16x32_bf16 v[34:37], v[202:205], v[194:197], v[132:135]
	v_mfma_f32_16x16x32_bf16 v[0:3], v[242:245], v[194:197], v[0:3]
	v_mfma_f32_16x16x32_bf16 v[6:9], v[150:153], v[146:149], v[6:9]
	v_mfma_f32_16x16x32_bf16 v[34:37], v[210:213], v[198:201], v[34:37]
	v_mfma_f32_16x16x32_bf16 v[0:3], v[150:153], v[198:201], v[0:3]
	s_setprio 0
	s_movk_i32 s5, 0x100
	v_cmp_gt_u32_e32 vcc, s5, v4
	s_barrier
	s_and_saveexec_b64 s[8:9], vcc
	s_cbranch_execz .LBB0_88
	s_barrier

; DI u16 f2bf(float x) { unsigned u = __float_as_uint(x); u += 0x7fffu + ((u >> 16) & 1u); return (u16)(u >> 16); }
; DI void phase_inproj(const Params& p, int layer, char* lds) {
;     ...
;     const int wr8 = w >> 2, wc8 = w & 3, fr = lane & 15, fq = lane >> 4;
; #pragma unroll
;     for (int bj = 0; bj < 2; ++bj)
; #pragma unroll
;       for (int n = 0; n < 2; ++n) {
;         const int cw = n0 + bj * 128 + wc8 * 32 + n * 16, col = cw + fr;
;         u16* dst = H + cw; int dstr = DIN;
;         {
;           const int bb = m0 / S;
;           if (cw >= C_DK && cw < C_DV) { const int o = cw - C_DK; dst = (u16*)(p.ws + OFF_DK) + ((size_t)(bb * 3 * S + (o >> 6) * S) << 6) + (o & 63); dstr = 64; }
;           else if (cw >= C_DV && cw < C_SQ) { const int o = cw - C_DV; dst = (u16*)(p.ws + OFF_DV) + ((size_t)(bb * 3 * S + (o >> 6) * S) << 6) + (o & 63); dstr = 64; }
;           else if (cw >= C_SK && cw < C_SV) { const int o = cw - C_SK; dst = (u16*)(p.ws + OFF_SK) + ((size_t)(bb * 1 * S + (o >> 6) * S) << 6) + (o & 63); dstr = 64; }
;           else if (cw >= C_SV && cw < C_GATE) { const int o = cw - C_SV; dst = (u16*)(p.ws + OFF_SV) + ((size_t)(bb * 1 * S + (o >> 6) * S) << 6) + (o & 63); dstr = 64; }
;         }
;         if (cw < DIN) {
;           float sc = 1.f;
;           if (col >= C_DQ && col < C_DK) sc = SC_DQ;
;           if (col >= C_SQ && col < C_SK) sc = SC_SQ;
;           const bool gate = col >= C_GATE;
; #pragma unroll
;           for (int ai = 0; ai < 2; ++ai)
; #pragma unroll
;             for (int m = 0; m < 4; ++m) {
; #pragma unroll
;               for (int j = 0; j < 4; ++j) {
;                 const int row = m0 + ai * 128 + wr8 * 64 + m * 16 + fq * 4 + j;
;                 float v = acc[ai][bj][m][n][j] * sc;
;                 if (gate) v = v * __builtin_amdgcn_rcpf(1.f + __expf(-v));
;                 dst[(size_t)row * dstr + fr] = f2bf(v);
.Lipf_none:
	s_nop 7
	v_and_b32_e32 v140, 64, v144
	v_add_u32_e32 v140, v140, v130
	v_bfe_u32 v141, v144, 2, 2
	v_lshlrev_b32_e32 v141, 4, v141
	v_mov_b32_e32 v142, 0x15c0
	v_mul_u32_u24_e32 v132, v140, v142
	v_add_u32_e32 v132, v132, v141
	v_lshl_add_u32 v133, v140, 7, v141
	v_readfirstlane_b32 s26, v131
	s_lshr_b32 s27, s4, 13
	s_add_u32 s25, s6, s26
	s_cmpk_ge_u32 s25, 2784
	s_cbranch_scc1 .Lipe0_done
	s_cmpk_ge_u32 s25, 1760
	s_cbranch_scc1 .Lipe0_gate
	s_cmpk_ge_u32 s25, 1632
	s_cbranch_scc1 .Lipe0_sv
	s_cmpk_ge_u32 s25, 1504
	s_cbranch_scc1 .Lipe0_sk
	s_cmpk_ge_u32 s25, 1120
	s_cbranch_scc1 .Lipe0_sq
	s_cmpk_ge_u32 s25, 864
	s_cbranch_scc1 .Lipe0_dv
	s_cmpk_ge_u32 s25, 608
	s_cbranch_scc1 .Lipe0_dk
	s_cmpk_ge_u32 s25, 352
	s_cbranch_scc1 .Lipe0_dq
	s_mul_i32 s10, s4, 0x15c0
	s_lshl_b32 s11, s25, 1
	s_add_u32 s10, s10, s11
	s_add_u32 s8, s50, s10
	s_addc_u32 s9, s51, 0
	v_cvt_pk_bf16_f32 v136, v126, v127
	v_cvt_pk_bf16_f32 v137, v128, v129
	v_cvt_pk_bf16_f32 v138, v94, v95
	v_cvt_pk_bf16_f32 v139, v96, v97
	s_nop 0
	v_permlane32_swap_b32_e32 v136, v138
	v_permlane32_swap_b32_e32 v137, v139
	s_nop 0
	v_permlane16_swap_b32_e32 v136, v138
	v_permlane16_swap_b32_e32 v137, v139
	global_store_dwordx4 v132, v[136:139], s[8:9]
	s_nop 1
	v_cvt_pk_bf16_f32 v136, v122, v123
	v_cvt_pk_bf16_f32 v137, v124, v125
	v_cvt_pk_bf16_f32 v138, v90, v91
	v_cvt_pk_bf16_f32 v139, v92, v93
	s_nop 0
	v_permlane32_swap_b32_e32 v136, v138
	v_permlane32_swap_b32_e32 v137, v139
	s_nop 0
	v_permlane16_swap_b32_e32 v136, v138
	v_permlane16_swap_b32_e32 v137, v139
	v_add_u32_e32 v134, 0x15c00, v132
	global_store_dwordx4 v134, v[136:139], s[8:9]
	s_nop 1
	v_cvt_pk_bf16_f32 v136, v118, v119
	v_cvt_pk_bf16_f32 v137, v120, v121
	v_cvt_pk_bf16_f32 v138, v86, v87
	v_cvt_pk_bf16_f32 v139, v88, v89
	s_nop 0
	v_permlane32_swap_b32_e32 v136, v138
	v_permlane32_swap_b32_e32 v137, v139
	s_nop 0
	v_permlane16_swap_b32_e32 v136, v138
	v_permlane16_swap_b32_e32 v137, v139
	v_add_u32_e32 v134, 0x2b800, v132
	global_store_dwordx4 v134, v[136:139], s[8:9]
	s_nop 1
	v_cvt_pk_bf16_f32 v136, v114, v115
	v_cvt_pk_bf16_f32 v137, v116, v117
	v_cvt_pk_bf16_f32 v138, v82, v83
	v_cvt_pk_bf16_f32 v139, v84, v85
	s_nop 0
	v_permlane32_swap_b32_e32 v136, v138
	v_permlane32_swap_b32_e32 v137, v139
	s_nop 0
	v_permlane16_swap_b32_e32 v136, v138
	v_permlane16_swap_b32_e32 v137, v139
	v_add_u32_e32 v134, 0x41400, v132
	global_store_dwordx4 v134, v[136:139], s[8:9]
	s_nop 1
	v_cvt_pk_bf16_f32 v136, v110, v111
	v_cvt_pk_bf16_f32 v137, v112, v113
	v_cvt_pk_bf16_f32 v138, v78, v79
	v_cvt_pk_bf16_f32 v139, v80, v81
	s_nop 0
	v_permlane32_swap_b32_e32 v136, v138
	v_permlane32_swap_b32_e32 v137, v139
	s_nop 0
	v_permlane16_swap_b32_e32 v136, v138
	v_permlane16_swap_b32_e32 v137, v139
	v_add_u32_e32 v134, 0xae000, v132
	global_store_dwordx4 v134, v[136:139], s[8:9]
	s_nop 1
	v_cvt_pk_bf16_f32 v136, v106, v107
	v_cvt_pk_bf16_f32 v137, v108, v109
	v_cvt_pk_bf16_f32 v138, v74, v75
	v_cvt_pk_bf16_f32 v139, v76, v77
	s_nop 0
	v_permlane32_swap_b32_e32 v136, v138
	v_permlane32_swap_b32_e32 v137, v139
	s_nop 0
	v_permlane16_swap_b32_e32 v136, v138
	v_permlane16_swap_b32_e32 v137, v139
	v_add_u32_e32 v134, 0xc3c00, v132
	global_store_dwordx4 v134, v[136:139], s[8:9]
	s_nop 1
	v_cvt_pk_bf16_f32 v136, v102, v103
	v_cvt_pk_bf16_f32 v137, v104, v105
	v_cvt_pk_bf16_f32 v138, v70, v71
	v_cvt_pk_bf16_f32 v139, v72, v73
	s_nop 0
	v_permlane32_swap_b32_e32 v136, v138
	v_permlane32_swap_b32_e32 v137, v139
	s_nop 0
	v_permlane16_swap_b32_e32 v136, v138
	v_permlane16_swap_b32_e32 v137, v139
	v_add_u32_e32 v134, 0xd9800, v132
	global_store_dwordx4 v134, v[136:139], s[8:9]
	s_nop 1
	v_cvt_pk_bf16_f32 v136, v98, v99
	v_cvt_pk_bf16_f32 v137, v100, v101
	v_cvt_pk_bf16_f32 v138, v66, v67
	v_cvt_pk_bf16_f32 v139, v68, v69
	s_nop 0
	v_permlane32_swap_b32_e32 v136, v138
	v_permlane32_swap_b32_e32 v137, v139
	s_nop 0
	v_permlane16_swap_b32_e32 v136, v138
	v_permlane16_swap_b32_e32 v137, v139
	v_add_u32_e32 v134, 0xef400, v132
	global_store_dwordx4 v134, v[136:139], s[8:9]
	s_nop 1
	s_branch .Lipe0_done

; DI u16 f2bf(float x) { unsigned u = __float_as_uint(x); u += 0x7fffu + ((u >> 16) & 1u); return (u16)(u >> 16); }
; DI void phase_inproj(const Params& p, int layer, char* lds) {
;     ...
;           float sc = 1.f;
;           if (col >= C_DQ && col < C_DK) sc = SC_DQ;
;           if (col >= C_SQ && col < C_SK) sc = SC_SQ;
;           const bool gate = col >= C_GATE;
; #pragma unroll
;           for (int ai = 0; ai < 2; ++ai)
; #pragma unroll
;             for (int m = 0; m < 4; ++m) {
; #pragma unroll
;               for (int j = 0; j < 4; ++j) {
;                 const int row = m0 + ai * 128 + wr8 * 64 + m * 16 + fq * 4 + j;
;                 float v = acc[ai][bj][m][n][j] * sc;
;                 if (gate) v = v * __builtin_amdgcn_rcpf(1.f + __expf(-v));
;                 dst[(size_t)row * dstr + fr] = f2bf(v);
.Lipe0_scaled:
	s_mul_i32 s10, s4, 0x15c0
	s_lshl_b32 s11, s25, 1
	s_add_u32 s10, s10, s11
	s_add_u32 s8, s50, s10
	s_addc_u32 s9, s51, 0
	v_mul_f32_e32 v126, v146, v126
	v_mul_f32_e32 v127, v146, v127
	v_mul_f32_e32 v128, v146, v128
	v_mul_f32_e32 v129, v146, v129
	v_mul_f32_e32 v94, v146, v94
	v_mul_f32_e32 v95, v146, v95
	v_mul_f32_e32 v96, v146, v96
	v_mul_f32_e32 v97, v146, v97
	v_cvt_pk_bf16_f32 v136, v126, v127
	v_cvt_pk_bf16_f32 v137, v128, v129
	v_cvt_pk_bf16_f32 v138, v94, v95
	v_cvt_pk_bf16_f32 v139, v96, v97
	s_nop 0
	v_permlane32_swap_b32_e32 v136, v138
	v_permlane32_swap_b32_e32 v137, v139
	s_nop 0
	v_permlane16_swap_b32_e32 v136, v138
	v_permlane16_swap_b32_e32 v137, v139
	global_store_dwordx4 v132, v[136:139], s[8:9]
	s_nop 1
	v_mul_f32_e32 v122, v146, v122
	v_mul_f32_e32 v123, v146, v123
	v_mul_f32_e32 v124, v146, v124
	v_mul_f32_e32 v125, v146, v125
	v_mul_f32_e32 v90, v146, v90
	v_mul_f32_e32 v91, v146, v91
	v_mul_f32_e32 v92, v146, v92
	v_mul_f32_e32 v93, v146, v93
	v_cvt_pk_bf16_f32 v136, v122, v123
	v_cvt_pk_bf16_f32 v137, v124, v125
	v_cvt_pk_bf16_f32 v138, v90, v91
	v_cvt_pk_bf16_f32 v139, v92, v93
	s_nop 0
	v_permlane32_swap_b32_e32 v136, v138
	v_permlane32_swap_b32_e32 v137, v139
	s_nop 0
	v_permlane16_swap_b32_e32 v136, v138
	v_permlane16_swap_b32_e32 v137, v139
	v_add_u32_e32 v134, 0x15c00, v132
	global_store_dwordx4 v134, v[136:139], s[8:9]
	s_nop 1
	v_mul_f32_e32 v118, v146, v118
	v_mul_f32_e32 v119, v146, v119
	v_mul_f32_e32 v120, v146, v120
	v_mul_f32_e32 v121, v146, v121
	v_mul_f32_e32 v86, v146, v86
	v_mul_f32_e32 v87, v146, v87
	v_mul_f32_e32 v88, v146, v88
	v_mul_f32_e32 v89, v146, v89
	v_cvt_pk_bf16_f32 v136, v118, v119
	v_cvt_pk_bf16_f32 v137, v120, v121
	v_cvt_pk_bf16_f32 v138, v86, v87
	v_cvt_pk_bf16_f32 v139, v88, v89
	s_nop 0
	v_permlane32_swap_b32_e32 v136, v138
	v_permlane32_swap_b32_e32 v137, v139
	s_nop 0
	v_permlane16_swap_b32_e32 v136, v138
	v_permlane16_swap_b32_e32 v137, v139
	v_add_u32_e32 v134, 0x2b800, v132
	global_store_dwordx4 v134, v[136:139], s[8:9]
	s_nop 1
	v_mul_f32_e32 v114, v146, v114
	v_mul_f32_e32 v115, v146, v115
	v_mul_f32_e32 v116, v146, v116
	v_mul_f32_e32 v117, v146, v117
	v_mul_f32_e32 v82, v146, v82
	v_mul_f32_e32 v83, v146, v83
	v_mul_f32_e32 v84, v146, v84
	v_mul_f32_e32 v85, v146, v85
	v_cvt_pk_bf16_f32 v136, v114, v115
	v_cvt_pk_bf16_f32 v137, v116, v117
	v_cvt_pk_bf16_f32 v138, v82, v83
	v_cvt_pk_bf16_f32 v139, v84, v85
	s_nop 0
	v_permlane32_swap_b32_e32 v136, v138
	v_permlane32_swap_b32_e32 v137, v139
	s_nop 0
	v_permlane16_swap_b32_e32 v136, v138
	v_permlane16_swap_b32_e32 v137, v139
	v_add_u32_e32 v134, 0x41400, v132
	global_store_dwordx4 v134, v[136:139], s[8:9]
	s_nop 1
	v_mul_f32_e32 v110, v146, v110
	v_mul_f32_e32 v111, v146, v111
	v_mul_f32_e32 v112, v146, v112
	v_mul_f32_e32 v113, v146, v113
	v_mul_f32_e32 v78, v146, v78
	v_mul_f32_e32 v79, v146, v79
	v_mul_f32_e32 v80, v146, v80
	v_mul_f32_e32 v81, v146, v81
	v_cvt_pk_bf16_f32 v136, v110, v111
	v_cvt_pk_bf16_f32 v137, v112, v113
	v_cvt_pk_bf16_f32 v138, v78, v79
	v_cvt_pk_bf16_f32 v139, v80, v81
	s_nop 0
	v_permlane32_swap_b32_e32 v136, v138
	v_permlane32_swap_b32_e32 v137, v139
	s_nop 0
	v_permlane16_swap_b32_e32 v136, v138
	v_permlane16_swap_b32_e32 v137, v139
	v_add_u32_e32 v134, 0xae000, v132
	global_store_dwordx4 v134, v[136:139], s[8:9]
	s_nop 1
	v_mul_f32_e32 v106, v146, v106
	v_mul_f32_e32 v107, v146, v107
	v_mul_f32_e32 v108, v146, v108
	v_mul_f32_e32 v109, v146, v109
	v_mul_f32_e32 v74, v146, v74
	v_mul_f32_e32 v75, v146, v75
	v_mul_f32_e32 v76, v146, v76
	v_mul_f32_e32 v77, v146, v77
	v_cvt_pk_bf16_f32 v136, v106, v107
	v_cvt_pk_bf16_f32 v137, v108, v109
	v_cvt_pk_bf16_f32 v138, v74, v75
	v_cvt_pk_bf16_f32 v139, v76, v77
	s_nop 0
	v_permlane32_swap_b32_e32 v136, v138
	v_permlane32_swap_b32_e32 v137, v139
	s_nop 0
	v_permlane16_swap_b32_e32 v136, v138
	v_permlane16_swap_b32_e32 v137, v139
	v_add_u32_e32 v134, 0xc3c00, v132
	global_store_dwordx4 v134, v[136:139], s[8:9]
	s_nop 1
	v_mul_f32_e32 v102, v146, v102
	v_mul_f32_e32 v103, v146, v103
	v_mul_f32_e32 v104, v146, v104
	v_mul_f32_e32 v105, v146, v105
	v_mul_f32_e32 v70, v146, v70
	v_mul_f32_e32 v71, v146, v71
	v_mul_f32_e32 v72, v146, v72
	v_mul_f32_e32 v73, v146, v73
	v_cvt_pk_bf16_f32 v136, v102, v103
	v_cvt_pk_bf16_f32 v137, v104, v105
	v_cvt_pk_bf16_f32 v138, v70, v71
	v_cvt_pk_bf16_f32 v139, v72, v73
	s_nop 0
	v_permlane32_swap_b32_e32 v136, v138
	v_permlane32_swap_b32_e32 v137, v139
	s_nop 0
	v_permlane16_swap_b32_e32 v136, v138
	v_permlane16_swap_b32_e32 v137, v139
	v_add_u32_e32 v134, 0xd9800, v132
	global_store_dwordx4 v134, v[136:139], s[8:9]
	s_nop 1
	v_mul_f32_e32 v98, v146, v98
	v_mul_f32_e32 v99, v146, v99
	v_mul_f32_e32 v100, v146, v100
	v_mul_f32_e32 v101, v146, v101
	v_mul_f32_e32 v66, v146, v66
	v_mul_f32_e32 v67, v146, v67
	v_mul_f32_e32 v68, v146, v68
	v_mul_f32_e32 v69, v146, v69
	v_cvt_pk_bf16_f32 v136, v98, v99
	v_cvt_pk_bf16_f32 v137, v100, v101
	v_cvt_pk_bf16_f32 v138, v66, v67
	v_cvt_pk_bf16_f32 v139, v68, v69
	s_nop 0
	v_permlane32_swap_b32_e32 v136, v138
	v_permlane32_swap_b32_e32 v137, v139
	s_nop 0
	v_permlane16_swap_b32_e32 v136, v138
	v_permlane16_swap_b32_e32 v137, v139
	v_add_u32_e32 v134, 0xef400, v132
	global_store_dwordx4 v134, v[136:139], s[8:9]
	s_nop 1
	s_branch .Lipe0_done
; DI u16 f2bf(float x) { unsigned u = __float_as_uint(x); u += 0x7fffu + ((u >> 16) & 1u); return (u16)(u >> 16); }
; DI void phase_inproj(const Params& p, int layer, char* lds) {
;     ...
;           const bool gate = col >= C_GATE;
; #pragma unroll
;           for (int ai = 0; ai < 2; ++ai)
; #pragma unroll
;             for (int m = 0; m < 4; ++m) {
; #pragma unroll
;               for (int j = 0; j < 4; ++j) {
;                 const int row = m0 + ai * 128 + wr8 * 64 + m * 16 + fq * 4 + j;
;                 float v = acc[ai][bj][m][n][j] * sc;
;                 if (gate) v = v * __builtin_amdgcn_rcpf(1.f + __expf(-v));
;                 dst[(size_t)row * dstr + fr] = f2bf(v);
.Lipe0_gate:
	s_mul_i32 s10, s4, 0x15c0
	s_lshl_b32 s11, s25, 1
	s_add_u32 s10, s10, s11
	s_add_u32 s8, s50, s10
	s_addc_u32 s9, s51, 0
	v_mul_f32_e32 v140, 0xbfb8aa3b, v126
	v_mul_f32_e32 v141, 0xbfb8aa3b, v127
	v_mul_f32_e32 v142, 0xbfb8aa3b, v128
	v_mul_f32_e32 v143, 0xbfb8aa3b, v129
	v_exp_f32_e32 v140, v140
	v_exp_f32_e32 v141, v141
	v_exp_f32_e32 v142, v142
	v_exp_f32_e32 v143, v143
	v_add_f32_e32 v140, 1.0, v140
	v_add_f32_e32 v141, 1.0, v141
	v_add_f32_e32 v142, 1.0, v142
	v_add_f32_e32 v143, 1.0, v143
	v_rcp_f32_e32 v140, v140
	v_rcp_f32_e32 v141, v141
	v_rcp_f32_e32 v142, v142
	v_rcp_f32_e32 v143, v143
	v_mul_f32_e32 v126, v126, v140
	v_mul_f32_e32 v127, v127, v141
	v_mul_f32_e32 v128, v128, v142
	v_mul_f32_e32 v129, v129, v143
	v_mul_f32_e32 v140, 0xbfb8aa3b, v94
	v_mul_f32_e32 v141, 0xbfb8aa3b, v95
	v_mul_f32_e32 v142, 0xbfb8aa3b, v96
	v_mul_f32_e32 v143, 0xbfb8aa3b, v97
	v_exp_f32_e32 v140, v140
	v_exp_f32_e32 v141, v141
	v_exp_f32_e32 v142, v142
	v_exp_f32_e32 v143, v143
	v_add_f32_e32 v140, 1.0, v140
	v_add_f32_e32 v141, 1.0, v141
	v_add_f32_e32 v142, 1.0, v142
	v_add_f32_e32 v143, 1.0, v143
	v_rcp_f32_e32 v140, v140
	v_rcp_f32_e32 v141, v141
	v_rcp_f32_e32 v142, v142
	v_rcp_f32_e32 v143, v143
	v_mul_f32_e32 v94, v94, v140
	v_mul_f32_e32 v95, v95, v141
	v_mul_f32_e32 v96, v96, v142
	v_mul_f32_e32 v97, v97, v143
	v_cvt_pk_bf16_f32 v136, v126, v127
	v_cvt_pk_bf16_f32 v137, v128, v129
	v_cvt_pk_bf16_f32 v138, v94, v95
	v_cvt_pk_bf16_f32 v139, v96, v97
	s_nop 0
	v_permlane32_swap_b32_e32 v136, v138
	v_permlane32_swap_b32_e32 v137, v139
	s_nop 0
	v_permlane16_swap_b32_e32 v136, v138
	v_permlane16_swap_b32_e32 v137, v139
	global_store_dwordx4 v132, v[136:139], s[8:9]
	s_nop 1
	v_mul_f32_e32 v140, 0xbfb8aa3b, v122
	v_mul_f32_e32 v141, 0xbfb8aa3b, v123
	v_mul_f32_e32 v142, 0xbfb8aa3b, v124
	v_mul_f32_e32 v143, 0xbfb8aa3b, v125
	v_exp_f32_e32 v140, v140
	v_exp_f32_e32 v141, v141
	v_exp_f32_e32 v142, v142
	v_exp_f32_e32 v143, v143
	v_add_f32_e32 v140, 1.0, v140
	v_add_f32_e32 v141, 1.0, v141
	v_add_f32_e32 v142, 1.0, v142
	v_add_f32_e32 v143, 1.0, v143
	v_rcp_f32_e32 v140, v140
	v_rcp_f32_e32 v141, v141
	v_rcp_f32_e32 v142, v142
	v_rcp_f32_e32 v143, v143
	v_mul_f32_e32 v122, v122, v140
	v_mul_f32_e32 v123, v123, v141
	v_mul_f32_e32 v124, v124, v142
	v_mul_f32_e32 v125, v125, v143
	v_mul_f32_e32 v140, 0xbfb8aa3b, v90
	v_mul_f32_e32 v141, 0xbfb8aa3b, v91
	v_mul_f32_e32 v142, 0xbfb8aa3b, v92
	v_mul_f32_e32 v143, 0xbfb8aa3b, v93
	v_exp_f32_e32 v140, v140
	v_exp_f32_e32 v141, v141
	v_exp_f32_e32 v142, v142
	v_exp_f32_e32 v143, v143
	v_add_f32_e32 v140, 1.0, v140
	v_add_f32_e32 v141, 1.0, v141
	v_add_f32_e32 v142, 1.0, v142
	v_add_f32_e32 v143, 1.0, v143
	v_rcp_f32_e32 v140, v140
	v_rcp_f32_e32 v141, v141
	v_rcp_f32_e32 v142, v142
	v_rcp_f32_e32 v143, v143
	v_mul_f32_e32 v90, v90, v140
	v_mul_f32_e32 v91, v91, v141
	v_mul_f32_e32 v92, v92, v142
	v_mul_f32_e32 v93, v93, v143
	v_cvt_pk_bf16_f32 v136, v122, v123
	v_cvt_pk_bf16_f32 v137, v124, v125
	v_cvt_pk_bf16_f32 v138, v90, v91
	v_cvt_pk_bf16_f32 v139, v92, v93
	s_nop 0
	v_permlane32_swap_b32_e32 v136, v138
	v_permlane32_swap_b32_e32 v137, v139
	s_nop 0
	v_permlane16_swap_b32_e32 v136, v138
	v_permlane16_swap_b32_e32 v137, v139
	v_add_u32_e32 v134, 0x15c00, v132
	global_store_dwordx4 v134, v[136:139], s[8:9]
	s_nop 1
	v_mul_f32_e32 v140, 0xbfb8aa3b, v118
	v_mul_f32_e32 v141, 0xbfb8aa3b, v119
	v_mul_f32_e32 v142, 0xbfb8aa3b, v120
	v_mul_f32_e32 v143, 0xbfb8aa3b, v121
	v_exp_f32_e32 v140, v140
	v_exp_f32_e32 v141, v141
	v_exp_f32_e32 v142, v142
	v_exp_f32_e32 v143, v143
	v_add_f32_e32 v140, 1.0, v140
	v_add_f32_e32 v141, 1.0, v141
	v_add_f32_e32 v142, 1.0, v142
	v_add_f32_e32 v143, 1.0, v143
	v_rcp_f32_e32 v140, v140
	v_rcp_f32_e32 v141, v141
	v_rcp_f32_e32 v142, v142
	v_rcp_f32_e32 v143, v143
	v_mul_f32_e32 v118, v118, v140
	v_mul_f32_e32 v119, v119, v141
	v_mul_f32_e32 v120, v120, v142
	v_mul_f32_e32 v121, v121, v143
	v_mul_f32_e32 v140, 0xbfb8aa3b, v86
	v_mul_f32_e32 v141, 0xbfb8aa3b, v87
	v_mul_f32_e32 v142, 0xbfb8aa3b, v88
	v_mul_f32_e32 v143, 0xbfb8aa3b, v89
	v_exp_f32_e32 v140, v140
	v_exp_f32_e32 v141, v141
	v_exp_f32_e32 v142, v142
	v_exp_f32_e32 v143, v143
	v_add_f32_e32 v140, 1.0, v140
	v_add_f32_e32 v141, 1.0, v141
	v_add_f32_e32 v142, 1.0, v142
	v_add_f32_e32 v143, 1.0, v143
	v_rcp_f32_e32 v140, v140
	v_rcp_f32_e32 v141, v141
	v_rcp_f32_e32 v142, v142
	v_rcp_f32_e32 v143, v143
	v_mul_f32_e32 v86, v86, v140
	v_mul_f32_e32 v87, v87, v141
	v_mul_f32_e32 v88, v88, v142
	v_mul_f32_e32 v89, v89, v143
	v_cvt_pk_bf16_f32 v136, v118, v119
	v_cvt_pk_bf16_f32 v137, v120, v121
	v_cvt_pk_bf16_f32 v138, v86, v87
	v_cvt_pk_bf16_f32 v139, v88, v89
	s_nop 0
	v_permlane32_swap_b32_e32 v136, v138
	v_permlane32_swap_b32_e32 v137, v139
	s_nop 0
	v_permlane16_swap_b32_e32 v136, v138
	v_permlane16_swap_b32_e32 v137, v139
	v_add_u32_e32 v134, 0x2b800, v132
	global_store_dwordx4 v134, v[136:139], s[8:9]
	s_nop 1
	v_mul_f32_e32 v140, 0xbfb8aa3b, v114
	v_mul_f32_e32 v141, 0xbfb8aa3b, v115
	v_mul_f32_e32 v142, 0xbfb8aa3b, v116
	v_mul_f32_e32 v143, 0xbfb8aa3b, v117
	v_exp_f32_e32 v140, v140
	v_exp_f32_e32 v141, v141
	v_exp_f32_e32 v142, v142
	v_exp_f32_e32 v143, v143
	v_add_f32_e32 v140, 1.0, v140
	v_add_f32_e32 v141, 1.0, v141
	v_add_f32_e32 v142, 1.0, v142
	v_add_f32_e32 v143, 1.0, v143
	v_rcp_f32_e32 v140, v140
	v_rcp_f32_e32 v141, v141
	v_rcp_f32_e32 v142, v142
	v_rcp_f32_e32 v143, v143
	v_mul_f32_e32 v114, v114, v140
	v_mul_f32_e32 v115, v115, v141
	v_mul_f32_e32 v116, v116, v142
	v_mul_f32_e32 v117, v117, v143
	v_mul_f32_e32 v140, 0xbfb8aa3b, v82
	v_mul_f32_e32 v141, 0xbfb8aa3b, v83
; DI u16 f2bf(float x) { unsigned u = __float_as_uint(x); u += 0x7fffu + ((u >> 16) & 1u); return (u16)(u >> 16); }
; DI void phase_inproj(const Params& p, int layer, char* lds) {
;     ...
;           const bool gate = col >= C_GATE;
; #pragma unroll
;           for (int ai = 0; ai < 2; ++ai)
; #pragma unroll
;             for (int m = 0; m < 4; ++m) {
; #pragma unroll
;               for (int j = 0; j < 4; ++j) {
;                 const int row = m0 + ai * 128 + wr8 * 64 + m * 16 + fq * 4 + j;
;                 float v = acc[ai][bj][m][n][j] * sc;
;                 if (gate) v = v * __builtin_amdgcn_rcpf(1.f + __expf(-v));
;                 dst[(size_t)row * dstr + fr] = f2bf(v);
	v_mul_f32_e32 v142, 0xbfb8aa3b, v84
	v_mul_f32_e32 v143, 0xbfb8aa3b, v85
	v_exp_f32_e32 v140, v140
	v_exp_f32_e32 v141, v141
	v_exp_f32_e32 v142, v142
	v_exp_f32_e32 v143, v143
	v_add_f32_e32 v140, 1.0, v140
	v_add_f32_e32 v141, 1.0, v141
	v_add_f32_e32 v142, 1.0, v142
	v_add_f32_e32 v143, 1.0, v143
	v_rcp_f32_e32 v140, v140
	v_rcp_f32_e32 v141, v141
	v_rcp_f32_e32 v142, v142
	v_rcp_f32_e32 v143, v143
	v_mul_f32_e32 v82, v82, v140
	v_mul_f32_e32 v83, v83, v141
	v_mul_f32_e32 v84, v84, v142
	v_mul_f32_e32 v85, v85, v143
	v_cvt_pk_bf16_f32 v136, v114, v115
	v_cvt_pk_bf16_f32 v137, v116, v117
	v_cvt_pk_bf16_f32 v138, v82, v83
	v_cvt_pk_bf16_f32 v139, v84, v85
	s_nop 0
	v_permlane32_swap_b32_e32 v136, v138
	v_permlane32_swap_b32_e32 v137, v139
	s_nop 0
	v_permlane16_swap_b32_e32 v136, v138
	v_permlane16_swap_b32_e32 v137, v139
	v_add_u32_e32 v134, 0x41400, v132
	global_store_dwordx4 v134, v[136:139], s[8:9]
	s_nop 1
	v_mul_f32_e32 v140, 0xbfb8aa3b, v110
	v_mul_f32_e32 v141, 0xbfb8aa3b, v111
	v_mul_f32_e32 v142, 0xbfb8aa3b, v112
	v_mul_f32_e32 v143, 0xbfb8aa3b, v113
	v_exp_f32_e32 v140, v140
	v_exp_f32_e32 v141, v141
	v_exp_f32_e32 v142, v142
	v_exp_f32_e32 v143, v143
	v_add_f32_e32 v140, 1.0, v140
	v_add_f32_e32 v141, 1.0, v141
	v_add_f32_e32 v142, 1.0, v142
	v_add_f32_e32 v143, 1.0, v143
	v_rcp_f32_e32 v140, v140
	v_rcp_f32_e32 v141, v141
	v_rcp_f32_e32 v142, v142
	v_rcp_f32_e32 v143, v143
	v_mul_f32_e32 v110, v110, v140
	v_mul_f32_e32 v111, v111, v141
	v_mul_f32_e32 v112, v112, v142
	v_mul_f32_e32 v113, v113, v143
	v_mul_f32_e32 v140, 0xbfb8aa3b, v78
	v_mul_f32_e32 v141, 0xbfb8aa3b, v79
	v_mul_f32_e32 v142, 0xbfb8aa3b, v80
	v_mul_f32_e32 v143, 0xbfb8aa3b, v81
	v_exp_f32_e32 v140, v140
	v_exp_f32_e32 v141, v141
	v_exp_f32_e32 v142, v142
	v_exp_f32_e32 v143, v143
	v_add_f32_e32 v140, 1.0, v140
	v_add_f32_e32 v141, 1.0, v141
	v_add_f32_e32 v142, 1.0, v142
	v_add_f32_e32 v143, 1.0, v143
	v_rcp_f32_e32 v140, v140
	v_rcp_f32_e32 v141, v141
	v_rcp_f32_e32 v142, v142
	v_rcp_f32_e32 v143, v143
	v_mul_f32_e32 v78, v78, v140
	v_mul_f32_e32 v79, v79, v141
	v_mul_f32_e32 v80, v80, v142
	v_mul_f32_e32 v81, v81, v143
	v_cvt_pk_bf16_f32 v136, v110, v111
	v_cvt_pk_bf16_f32 v137, v112, v113
	v_cvt_pk_bf16_f32 v138, v78, v79
	v_cvt_pk_bf16_f32 v139, v80, v81
	s_nop 0
	v_permlane32_swap_b32_e32 v136, v138
	v_permlane32_swap_b32_e32 v137, v139
	s_nop 0
	v_permlane16_swap_b32_e32 v136, v138
	v_permlane16_swap_b32_e32 v137, v139
	v_add_u32_e32 v134, 0xae000, v132
	global_store_dwordx4 v134, v[136:139], s[8:9]
	s_nop 1
	v_mul_f32_e32 v140, 0xbfb8aa3b, v106
	v_mul_f32_e32 v141, 0xbfb8aa3b, v107
	v_mul_f32_e32 v142, 0xbfb8aa3b, v108
	v_mul_f32_e32 v143, 0xbfb8aa3b, v109
	v_exp_f32_e32 v140, v140
	v_exp_f32_e32 v141, v141
	v_exp_f32_e32 v142, v142
	v_exp_f32_e32 v143, v143
	v_add_f32_e32 v140, 1.0, v140
	v_add_f32_e32 v141, 1.0, v141
	v_add_f32_e32 v142, 1.0, v142
	v_add_f32_e32 v143, 1.0, v143
	v_rcp_f32_e32 v140, v140
	v_rcp_f32_e32 v141, v141
	v_rcp_f32_e32 v142, v142
	v_rcp_f32_e32 v143, v143
	v_mul_f32_e32 v106, v106, v140
	v_mul_f32_e32 v107, v107, v141
	v_mul_f32_e32 v108, v108, v142
	v_mul_f32_e32 v109, v109, v143
	v_mul_f32_e32 v140, 0xbfb8aa3b, v74
	v_mul_f32_e32 v141, 0xbfb8aa3b, v75
	v_mul_f32_e32 v142, 0xbfb8aa3b, v76
	v_mul_f32_e32 v143, 0xbfb8aa3b, v77
	v_exp_f32_e32 v140, v140
	v_exp_f32_e32 v141, v141
	v_exp_f32_e32 v142, v142
	v_exp_f32_e32 v143, v143
	v_add_f32_e32 v140, 1.0, v140
	v_add_f32_e32 v141, 1.0, v141
	v_add_f32_e32 v142, 1.0, v142
	v_add_f32_e32 v143, 1.0, v143
	v_rcp_f32_e32 v140, v140
	v_rcp_f32_e32 v141, v141
	v_rcp_f32_e32 v142, v142
	v_rcp_f32_e32 v143, v143
	v_mul_f32_e32 v74, v74, v140
	v_mul_f32_e32 v75, v75, v141
; DI u16 f2bf(float x) { unsigned u = __float_as_uint(x); u += 0x7fffu + ((u >> 16) & 1u); return (u16)(u >> 16); }
; DI void phase_inproj(const Params& p, int layer, char* lds) {
;     ...
;           const bool gate = col >= C_GATE;
; #pragma unroll
;           for (int ai = 0; ai < 2; ++ai)
; #pragma unroll
;             for (int m = 0; m < 4; ++m) {
; #pragma unroll
;               for (int j = 0; j < 4; ++j) {
;                 const int row = m0 + ai * 128 + wr8 * 64 + m * 16 + fq * 4 + j;
;                 float v = acc[ai][bj][m][n][j] * sc;
;                 if (gate) v = v * __builtin_amdgcn_rcpf(1.f + __expf(-v));
;                 dst[(size_t)row * dstr + fr] = f2bf(v);
	v_mul_f32_e32 v76, v76, v142
	v_mul_f32_e32 v77, v77, v143
	v_cvt_pk_bf16_f32 v136, v106, v107
	v_cvt_pk_bf16_f32 v137, v108, v109
	v_cvt_pk_bf16_f32 v138, v74, v75
	v_cvt_pk_bf16_f32 v139, v76, v77
	s_nop 0
	v_permlane32_swap_b32_e32 v136, v138
	v_permlane32_swap_b32_e32 v137, v139
	s_nop 0
	v_permlane16_swap_b32_e32 v136, v138
	v_permlane16_swap_b32_e32 v137, v139
	v_add_u32_e32 v134, 0xc3c00, v132
	global_store_dwordx4 v134, v[136:139], s[8:9]
	s_nop 1
	v_mul_f32_e32 v140, 0xbfb8aa3b, v102
	v_mul_f32_e32 v141, 0xbfb8aa3b, v103
	v_mul_f32_e32 v142, 0xbfb8aa3b, v104
	v_mul_f32_e32 v143, 0xbfb8aa3b, v105
	v_exp_f32_e32 v140, v140
	v_exp_f32_e32 v141, v141
	v_exp_f32_e32 v142, v142
	v_exp_f32_e32 v143, v143
	v_add_f32_e32 v140, 1.0, v140
	v_add_f32_e32 v141, 1.0, v141
	v_add_f32_e32 v142, 1.0, v142
	v_add_f32_e32 v143, 1.0, v143
	v_rcp_f32_e32 v140, v140
	v_rcp_f32_e32 v141, v141
	v_rcp_f32_e32 v142, v142
	v_rcp_f32_e32 v143, v143
	v_mul_f32_e32 v102, v102, v140
	v_mul_f32_e32 v103, v103, v141
	v_mul_f32_e32 v104, v104, v142
	v_mul_f32_e32 v105, v105, v143
	v_mul_f32_e32 v140, 0xbfb8aa3b, v70
	v_mul_f32_e32 v141, 0xbfb8aa3b, v71
	v_mul_f32_e32 v142, 0xbfb8aa3b, v72
	v_mul_f32_e32 v143, 0xbfb8aa3b, v73
	v_exp_f32_e32 v140, v140
	v_exp_f32_e32 v141, v141
	v_exp_f32_e32 v142, v142
	v_exp_f32_e32 v143, v143
	v_add_f32_e32 v140, 1.0, v140
	v_add_f32_e32 v141, 1.0, v141
	v_add_f32_e32 v142, 1.0, v142
	v_add_f32_e32 v143, 1.0, v143
	v_rcp_f32_e32 v140, v140
	v_rcp_f32_e32 v141, v141
	v_rcp_f32_e32 v142, v142
	v_rcp_f32_e32 v143, v143
	v_mul_f32_e32 v70, v70, v140
	v_mul_f32_e32 v71, v71, v141
	v_mul_f32_e32 v72, v72, v142
	v_mul_f32_e32 v73, v73, v143
	v_cvt_pk_bf16_f32 v136, v102, v103
	v_cvt_pk_bf16_f32 v137, v104, v105
	v_cvt_pk_bf16_f32 v138, v70, v71
	v_cvt_pk_bf16_f32 v139, v72, v73
	s_nop 0
	v_permlane32_swap_b32_e32 v136, v138
	v_permlane32_swap_b32_e32 v137, v139
	s_nop 0
	v_permlane16_swap_b32_e32 v136, v138
	v_permlane16_swap_b32_e32 v137, v139
	v_add_u32_e32 v134, 0xd9800, v132
	global_store_dwordx4 v134, v[136:139], s[8:9]
	s_nop 1
	v_mul_f32_e32 v140, 0xbfb8aa3b, v98
	v_mul_f32_e32 v141, 0xbfb8aa3b, v99
	v_mul_f32_e32 v142, 0xbfb8aa3b, v100
	v_mul_f32_e32 v143, 0xbfb8aa3b, v101
	v_exp_f32_e32 v140, v140
	v_exp_f32_e32 v141, v141
	v_exp_f32_e32 v142, v142
	v_exp_f32_e32 v143, v143
	v_add_f32_e32 v140, 1.0, v140
	v_add_f32_e32 v141, 1.0, v141
	v_add_f32_e32 v142, 1.0, v142
	v_add_f32_e32 v143, 1.0, v143
	v_rcp_f32_e32 v140, v140
	v_rcp_f32_e32 v141, v141
	v_rcp_f32_e32 v142, v142
	v_rcp_f32_e32 v143, v143
	v_mul_f32_e32 v98, v98, v140
	v_mul_f32_e32 v99, v99, v141
	v_mul_f32_e32 v100, v100, v142
	v_mul_f32_e32 v101, v101, v143
	v_mul_f32_e32 v140, 0xbfb8aa3b, v66
	v_mul_f32_e32 v141, 0xbfb8aa3b, v67
	v_mul_f32_e32 v142, 0xbfb8aa3b, v68
	v_mul_f32_e32 v143, 0xbfb8aa3b, v69
	v_exp_f32_e32 v140, v140
	v_exp_f32_e32 v141, v141
	v_exp_f32_e32 v142, v142
	v_exp_f32_e32 v143, v143
	v_add_f32_e32 v140, 1.0, v140
	v_add_f32_e32 v141, 1.0, v141
	v_add_f32_e32 v142, 1.0, v142
	v_add_f32_e32 v143, 1.0, v143
	v_rcp_f32_e32 v140, v140
	v_rcp_f32_e32 v141, v141
	v_rcp_f32_e32 v142, v142
	v_rcp_f32_e32 v143, v143
	v_mul_f32_e32 v66, v66, v140
	v_mul_f32_e32 v67, v67, v141
	v_mul_f32_e32 v68, v68, v142
	v_mul_f32_e32 v69, v69, v143
	v_cvt_pk_bf16_f32 v136, v98, v99
	v_cvt_pk_bf16_f32 v137, v100, v101
	v_cvt_pk_bf16_f32 v138, v66, v67
	v_cvt_pk_bf16_f32 v139, v68, v69
	s_nop 0
	v_permlane32_swap_b32_e32 v136, v138
	v_permlane32_swap_b32_e32 v137, v139
	s_nop 0
	v_permlane16_swap_b32_e32 v136, v138
	v_permlane16_swap_b32_e32 v137, v139
	v_add_u32_e32 v134, 0xef400, v132
	global_store_dwordx4 v134, v[136:139], s[8:9]
	s_nop 1
	s_branch .Lipe0_done

; DI u16 f2bf(float x) { unsigned u = __float_as_uint(x); u += 0x7fffu + ((u >> 16) & 1u); return (u16)(u >> 16); }
; DI void phase_inproj(const Params& p, int layer, char* lds) {
;     ...
;           if (cw >= C_DK && cw < C_DV) { const int o = cw - C_DK; dst = (u16*)(p.ws + OFF_DK) + ((size_t)(bb * 3 * S + (o >> 6) * S) << 6) + (o & 63); dstr = 64; }
;           else if (cw >= C_DV && cw < C_SQ) { const int o = cw - C_DV; dst = (u16*)(p.ws + OFF_DV) + ((size_t)(bb * 3 * S + (o >> 6) * S) << 6) + (o & 63); dstr = 64; }
;           else if (cw >= C_SK && cw < C_SV) { const int o = cw - C_SK; dst = (u16*)(p.ws + OFF_SK) + ((size_t)(bb * 1 * S + (o >> 6) * S) << 6) + (o & 63); dstr = 64; }
;           else if (cw >= C_SV && cw < C_GATE) { const int o = cw - C_SV; dst = (u16*)(p.ws + OFF_SV) + ((size_t)(bb * 1 * S + (o >> 6) * S) << 6) + (o & 63); dstr = 64; }
;         }
;         if (cw < DIN) {
;           float sc = 1.f;
;           if (col >= C_DQ && col < C_DK) sc = SC_DQ;
;           if (col >= C_SQ && col < C_SK) sc = SC_SQ;
;           const bool gate = col >= C_GATE;
; #pragma unroll
;           for (int ai = 0; ai < 2; ++ai)
; #pragma unroll
;             for (int m = 0; m < 4; ++m) {
; #pragma unroll
;               for (int j = 0; j < 4; ++j) {
;                 const int row = m0 + ai * 128 + wr8 * 64 + m * 16 + fq * 4 + j;
;                 float v = acc[ai][bj][m][n][j] * sc;
;                 if (gate) v = v * __builtin_amdgcn_rcpf(1.f + __expf(-v));
;                 dst[(size_t)row * dstr + fr] = f2bf(v);
.Lipe0_kv:
	v_cvt_pk_bf16_f32 v136, v126, v127
	v_cvt_pk_bf16_f32 v137, v128, v129
	v_cvt_pk_bf16_f32 v138, v94, v95
	v_cvt_pk_bf16_f32 v139, v96, v97
	s_nop 0
	v_permlane32_swap_b32_e32 v136, v138
	v_permlane32_swap_b32_e32 v137, v139
	s_nop 0
	v_permlane16_swap_b32_e32 v136, v138
	v_permlane16_swap_b32_e32 v137, v139
	global_store_dwordx4 v133, v[136:139], s[8:9]
	s_nop 1
	v_cvt_pk_bf16_f32 v136, v122, v123
	v_cvt_pk_bf16_f32 v137, v124, v125
	v_cvt_pk_bf16_f32 v138, v90, v91
	v_cvt_pk_bf16_f32 v139, v92, v93
	s_nop 0
	v_permlane32_swap_b32_e32 v136, v138
	v_permlane32_swap_b32_e32 v137, v139
	s_nop 0
	v_permlane16_swap_b32_e32 v136, v138
	v_permlane16_swap_b32_e32 v137, v139
	v_add_u32_e32 v134, 0x800, v133
	global_store_dwordx4 v134, v[136:139], s[8:9]
	s_nop 1
	v_cvt_pk_bf16_f32 v136, v118, v119
	v_cvt_pk_bf16_f32 v137, v120, v121
	v_cvt_pk_bf16_f32 v138, v86, v87
	v_cvt_pk_bf16_f32 v139, v88, v89
	s_nop 0
	v_permlane32_swap_b32_e32 v136, v138
	v_permlane32_swap_b32_e32 v137, v139
	s_nop 0
	v_permlane16_swap_b32_e32 v136, v138
	v_permlane16_swap_b32_e32 v137, v139
	v_add_u32_e32 v134, 0x1000, v133
	global_store_dwordx4 v134, v[136:139], s[8:9]
	s_nop 1
	v_cvt_pk_bf16_f32 v136, v114, v115
	v_cvt_pk_bf16_f32 v137, v116, v117
	v_cvt_pk_bf16_f32 v138, v82, v83
	v_cvt_pk_bf16_f32 v139, v84, v85
	s_nop 0
	v_permlane32_swap_b32_e32 v136, v138
	v_permlane32_swap_b32_e32 v137, v139
	s_nop 0
	v_permlane16_swap_b32_e32 v136, v138
	v_permlane16_swap_b32_e32 v137, v139
	v_add_u32_e32 v134, 0x1800, v133
	global_store_dwordx4 v134, v[136:139], s[8:9]
	s_nop 1
	v_cvt_pk_bf16_f32 v136, v110, v111
	v_cvt_pk_bf16_f32 v137, v112, v113
	v_cvt_pk_bf16_f32 v138, v78, v79
	v_cvt_pk_bf16_f32 v139, v80, v81
	s_nop 0
	v_permlane32_swap_b32_e32 v136, v138
	v_permlane32_swap_b32_e32 v137, v139
	s_nop 0
	v_permlane16_swap_b32_e32 v136, v138
	v_permlane16_swap_b32_e32 v137, v139
	v_add_u32_e32 v134, 0x4000, v133
	global_store_dwordx4 v134, v[136:139], s[8:9]
	s_nop 1
	v_cvt_pk_bf16_f32 v136, v106, v107
	v_cvt_pk_bf16_f32 v137, v108, v109
	v_cvt_pk_bf16_f32 v138, v74, v75
	v_cvt_pk_bf16_f32 v139, v76, v77
	s_nop 0
	v_permlane32_swap_b32_e32 v136, v138
	v_permlane32_swap_b32_e32 v137, v139
	s_nop 0
	v_permlane16_swap_b32_e32 v136, v138
	v_permlane16_swap_b32_e32 v137, v139
	v_add_u32_e32 v134, 0x4800, v133
	global_store_dwordx4 v134, v[136:139], s[8:9]
	s_nop 1
	v_cvt_pk_bf16_f32 v136, v102, v103
	v_cvt_pk_bf16_f32 v137, v104, v105
	v_cvt_pk_bf16_f32 v138, v70, v71
	v_cvt_pk_bf16_f32 v139, v72, v73
	s_nop 0
	v_permlane32_swap_b32_e32 v136, v138
	v_permlane32_swap_b32_e32 v137, v139
	s_nop 0
	v_permlane16_swap_b32_e32 v136, v138
	v_permlane16_swap_b32_e32 v137, v139
	v_add_u32_e32 v134, 0x5000, v133
	global_store_dwordx4 v134, v[136:139], s[8:9]
	s_nop 1
	v_cvt_pk_bf16_f32 v136, v98, v99
	v_cvt_pk_bf16_f32 v137, v100, v101
	v_cvt_pk_bf16_f32 v138, v66, v67
	v_cvt_pk_bf16_f32 v139, v68, v69
	s_nop 0
	v_permlane32_swap_b32_e32 v136, v138
	v_permlane32_swap_b32_e32 v137, v139
	s_nop 0
	v_permlane16_swap_b32_e32 v136, v138
	v_permlane16_swap_b32_e32 v137, v139
	v_add_u32_e32 v134, 0x5800, v133
	global_store_dwordx4 v134, v[136:139], s[8:9]
	s_nop 1
.Lipe0_done:
	s_add_u32 s25, s6, s26
	s_add_u32 s25, s25, 128
	s_cmpk_ge_u32 s25, 2784
	s_cbranch_scc1 .Lipe1_done
	s_cmpk_ge_u32 s25, 1760
	s_cbranch_scc1 .Lipe1_gate
	s_cmpk_ge_u32 s25, 1632
	s_cbranch_scc1 .Lipe1_sv
	s_cmpk_ge_u32 s25, 1504
	s_cbranch_scc1 .Lipe1_sk
	s_cmpk_ge_u32 s25, 1120
	s_cbranch_scc1 .Lipe1_sq
	s_cmpk_ge_u32 s25, 864
	s_cbranch_scc1 .Lipe1_dv
	s_cmpk_ge_u32 s25, 608
	s_cbranch_scc1 .Lipe1_dk
	s_cmpk_ge_u32 s25, 352
	s_cbranch_scc1 .Lipe1_dq
	s_mul_i32 s10, s4, 0x15c0
	s_lshl_b32 s11, s25, 1
	s_add_u32 s10, s10, s11
	s_add_u32 s8, s50, s10
	s_addc_u32 s9, s51, 0
	v_cvt_pk_bf16_f32 v136, v62, v63
	v_cvt_pk_bf16_f32 v137, v64, v65
	v_cvt_pk_bf16_f32 v138, v30, v31
	v_cvt_pk_bf16_f32 v139, v32, v33
	s_nop 0
	v_permlane32_swap_b32_e32 v136, v138
	v_permlane32_swap_b32_e32 v137, v139
	s_nop 0
	v_permlane16_swap_b32_e32 v136, v138
	v_permlane16_swap_b32_e32 v137, v139
	global_store_dwordx4 v132, v[136:139], s[8:9]
	s_nop 1
	v_cvt_pk_bf16_f32 v136, v58, v59
	v_cvt_pk_bf16_f32 v137, v60, v61
	v_cvt_pk_bf16_f32 v138, v26, v27
	v_cvt_pk_bf16_f32 v139, v28, v29
	s_nop 0
	v_permlane32_swap_b32_e32 v136, v138
	v_permlane32_swap_b32_e32 v137, v139
	s_nop 0
	v_permlane16_swap_b32_e32 v136, v138
	v_permlane16_swap_b32_e32 v137, v139
	v_add_u32_e32 v134, 0x15c00, v132
	global_store_dwordx4 v134, v[136:139], s[8:9]
	s_nop 1
	v_cvt_pk_bf16_f32 v136, v54, v55
	v_cvt_pk_bf16_f32 v137, v56, v57
	v_cvt_pk_bf16_f32 v138, v22, v23
	v_cvt_pk_bf16_f32 v139, v24, v25
	s_nop 0
	v_permlane32_swap_b32_e32 v136, v138
	v_permlane32_swap_b32_e32 v137, v139
	s_nop 0
	v_permlane16_swap_b32_e32 v136, v138
	v_permlane16_swap_b32_e32 v137, v139
	v_add_u32_e32 v134, 0x2b800, v132
	global_store_dwordx4 v134, v[136:139], s[8:9]
	s_nop 1
	v_cvt_pk_bf16_f32 v136, v50, v51
	v_cvt_pk_bf16_f32 v137, v52, v53
	v_cvt_pk_bf16_f32 v138, v18, v19
	v_cvt_pk_bf16_f32 v139, v20, v21
	s_nop 0
	v_permlane32_swap_b32_e32 v136, v138
	v_permlane32_swap_b32_e32 v137, v139
	s_nop 0
	v_permlane16_swap_b32_e32 v136, v138
	v_permlane16_swap_b32_e32 v137, v139
	v_add_u32_e32 v134, 0x41400, v132
	global_store_dwordx4 v134, v[136:139], s[8:9]
	s_nop 1
	v_cvt_pk_bf16_f32 v136, v46, v47
	v_cvt_pk_bf16_f32 v137, v48, v49
	v_cvt_pk_bf16_f32 v138, v14, v15
	v_cvt_pk_bf16_f32 v139, v16, v17
	s_nop 0
	v_permlane32_swap_b32_e32 v136, v138
	v_permlane32_swap_b32_e32 v137, v139
	s_nop 0
	v_permlane16_swap_b32_e32 v136, v138
	v_permlane16_swap_b32_e32 v137, v139
	v_add_u32_e32 v134, 0xae000, v132
	global_store_dwordx4 v134, v[136:139], s[8:9]
	s_nop 1
	v_cvt_pk_bf16_f32 v136, v42, v43
	v_cvt_pk_bf16_f32 v137, v44, v45
	v_cvt_pk_bf16_f32 v138, v10, v11
	v_cvt_pk_bf16_f32 v139, v12, v13
	s_nop 0
	v_permlane32_swap_b32_e32 v136, v138
	v_permlane32_swap_b32_e32 v137, v139
	s_nop 0
	v_permlane16_swap_b32_e32 v136, v138
	v_permlane16_swap_b32_e32 v137, v139
	v_add_u32_e32 v134, 0xc3c00, v132
	global_store_dwordx4 v134, v[136:139], s[8:9]
	s_nop 1
	v_cvt_pk_bf16_f32 v136, v38, v39
	v_cvt_pk_bf16_f32 v137, v40, v41
	v_cvt_pk_bf16_f32 v138, v6, v7
	v_cvt_pk_bf16_f32 v139, v8, v9
	s_nop 0
	v_permlane32_swap_b32_e32 v136, v138
	v_permlane32_swap_b32_e32 v137, v139
	s_nop 0
	v_permlane16_swap_b32_e32 v136, v138
	v_permlane16_swap_b32_e32 v137, v139
	v_add_u32_e32 v134, 0xd9800, v132
	global_store_dwordx4 v134, v[136:139], s[8:9]
	s_nop 1
	v_cvt_pk_bf16_f32 v136, v34, v35
	v_cvt_pk_bf16_f32 v137, v36, v37
	v_cvt_pk_bf16_f32 v138, v0, v1
	v_cvt_pk_bf16_f32 v139, v2, v3
	s_nop 0
	v_permlane32_swap_b32_e32 v136, v138
	v_permlane32_swap_b32_e32 v137, v139
	s_nop 0
	v_permlane16_swap_b32_e32 v136, v138
	v_permlane16_swap_b32_e32 v137, v139
	v_add_u32_e32 v134, 0xef400, v132
	global_store_dwordx4 v134, v[136:139], s[8:9]
	s_nop 1
	s_branch .Lipe1_done

; DI u16 f2bf(float x) { unsigned u = __float_as_uint(x); u += 0x7fffu + ((u >> 16) & 1u); return (u16)(u >> 16); }
; DI void phase_inproj(const Params& p, int layer, char* lds) {
;     ...
;           float sc = 1.f;
;           if (col >= C_DQ && col < C_DK) sc = SC_DQ;
;           if (col >= C_SQ && col < C_SK) sc = SC_SQ;
;           const bool gate = col >= C_GATE;
; #pragma unroll
;           for (int ai = 0; ai < 2; ++ai)
; #pragma unroll
;             for (int m = 0; m < 4; ++m) {
; #pragma unroll
;               for (int j = 0; j < 4; ++j) {
;                 const int row = m0 + ai * 128 + wr8 * 64 + m * 16 + fq * 4 + j;
;                 float v = acc[ai][bj][m][n][j] * sc;
;                 if (gate) v = v * __builtin_amdgcn_rcpf(1.f + __expf(-v));
;                 dst[(size_t)row * dstr + fr] = f2bf(v);
.Lipe1_scaled:
	s_mul_i32 s10, s4, 0x15c0
	s_lshl_b32 s11, s25, 1
	s_add_u32 s10, s10, s11
	s_add_u32 s8, s50, s10
	s_addc_u32 s9, s51, 0
	v_mul_f32_e32 v62, v146, v62
	v_mul_f32_e32 v63, v146, v63
	v_mul_f32_e32 v64, v146, v64
	v_mul_f32_e32 v65, v146, v65
	v_mul_f32_e32 v30, v146, v30
	v_mul_f32_e32 v31, v146, v31
	v_mul_f32_e32 v32, v146, v32
	v_mul_f32_e32 v33, v146, v33
	v_cvt_pk_bf16_f32 v136, v62, v63
	v_cvt_pk_bf16_f32 v137, v64, v65
	v_cvt_pk_bf16_f32 v138, v30, v31
	v_cvt_pk_bf16_f32 v139, v32, v33
	s_nop 0
	v_permlane32_swap_b32_e32 v136, v138
	v_permlane32_swap_b32_e32 v137, v139
	s_nop 0
	v_permlane16_swap_b32_e32 v136, v138
	v_permlane16_swap_b32_e32 v137, v139
	global_store_dwordx4 v132, v[136:139], s[8:9]
	s_nop 1
	v_mul_f32_e32 v58, v146, v58
	v_mul_f32_e32 v59, v146, v59
	v_mul_f32_e32 v60, v146, v60
	v_mul_f32_e32 v61, v146, v61
	v_mul_f32_e32 v26, v146, v26
	v_mul_f32_e32 v27, v146, v27
	v_mul_f32_e32 v28, v146, v28
	v_mul_f32_e32 v29, v146, v29
	v_cvt_pk_bf16_f32 v136, v58, v59
	v_cvt_pk_bf16_f32 v137, v60, v61
	v_cvt_pk_bf16_f32 v138, v26, v27
	v_cvt_pk_bf16_f32 v139, v28, v29
	s_nop 0
	v_permlane32_swap_b32_e32 v136, v138
	v_permlane32_swap_b32_e32 v137, v139
	s_nop 0
	v_permlane16_swap_b32_e32 v136, v138
	v_permlane16_swap_b32_e32 v137, v139
	v_add_u32_e32 v134, 0x15c00, v132
	global_store_dwordx4 v134, v[136:139], s[8:9]
	s_nop 1
	v_mul_f32_e32 v54, v146, v54
	v_mul_f32_e32 v55, v146, v55
	v_mul_f32_e32 v56, v146, v56
	v_mul_f32_e32 v57, v146, v57
	v_mul_f32_e32 v22, v146, v22
	v_mul_f32_e32 v23, v146, v23
	v_mul_f32_e32 v24, v146, v24
	v_mul_f32_e32 v25, v146, v25
	v_cvt_pk_bf16_f32 v136, v54, v55
	v_cvt_pk_bf16_f32 v137, v56, v57
	v_cvt_pk_bf16_f32 v138, v22, v23
	v_cvt_pk_bf16_f32 v139, v24, v25
	s_nop 0
	v_permlane32_swap_b32_e32 v136, v138
	v_permlane32_swap_b32_e32 v137, v139
	s_nop 0
	v_permlane16_swap_b32_e32 v136, v138
	v_permlane16_swap_b32_e32 v137, v139
	v_add_u32_e32 v134, 0x2b800, v132
	global_store_dwordx4 v134, v[136:139], s[8:9]
	s_nop 1
	v_mul_f32_e32 v50, v146, v50
	v_mul_f32_e32 v51, v146, v51
	v_mul_f32_e32 v52, v146, v52
	v_mul_f32_e32 v53, v146, v53
	v_mul_f32_e32 v18, v146, v18
	v_mul_f32_e32 v19, v146, v19
	v_mul_f32_e32 v20, v146, v20
	v_mul_f32_e32 v21, v146, v21
	v_cvt_pk_bf16_f32 v136, v50, v51
	v_cvt_pk_bf16_f32 v137, v52, v53
	v_cvt_pk_bf16_f32 v138, v18, v19
	v_cvt_pk_bf16_f32 v139, v20, v21
	s_nop 0
	v_permlane32_swap_b32_e32 v136, v138
	v_permlane32_swap_b32_e32 v137, v139
	s_nop 0
	v_permlane16_swap_b32_e32 v136, v138
	v_permlane16_swap_b32_e32 v137, v139
	v_add_u32_e32 v134, 0x41400, v132
	global_store_dwordx4 v134, v[136:139], s[8:9]
	s_nop 1
	v_mul_f32_e32 v46, v146, v46
	v_mul_f32_e32 v47, v146, v47
	v_mul_f32_e32 v48, v146, v48
	v_mul_f32_e32 v49, v146, v49
	v_mul_f32_e32 v14, v146, v14
	v_mul_f32_e32 v15, v146, v15
	v_mul_f32_e32 v16, v146, v16
	v_mul_f32_e32 v17, v146, v17
	v_cvt_pk_bf16_f32 v136, v46, v47
	v_cvt_pk_bf16_f32 v137, v48, v49
	v_cvt_pk_bf16_f32 v138, v14, v15
	v_cvt_pk_bf16_f32 v139, v16, v17
	s_nop 0
	v_permlane32_swap_b32_e32 v136, v138
	v_permlane32_swap_b32_e32 v137, v139
	s_nop 0
	v_permlane16_swap_b32_e32 v136, v138
	v_permlane16_swap_b32_e32 v137, v139
	v_add_u32_e32 v134, 0xae000, v132
	global_store_dwordx4 v134, v[136:139], s[8:9]
	s_nop 1
	v_mul_f32_e32 v42, v146, v42
	v_mul_f32_e32 v43, v146, v43
	v_mul_f32_e32 v44, v146, v44
	v_mul_f32_e32 v45, v146, v45
	v_mul_f32_e32 v10, v146, v10
	v_mul_f32_e32 v11, v146, v11
	v_mul_f32_e32 v12, v146, v12
	v_mul_f32_e32 v13, v146, v13
	v_cvt_pk_bf16_f32 v136, v42, v43
	v_cvt_pk_bf16_f32 v137, v44, v45
	v_cvt_pk_bf16_f32 v138, v10, v11
	v_cvt_pk_bf16_f32 v139, v12, v13
	s_nop 0
	v_permlane32_swap_b32_e32 v136, v138
	v_permlane32_swap_b32_e32 v137, v139
	s_nop 0
	v_permlane16_swap_b32_e32 v136, v138
	v_permlane16_swap_b32_e32 v137, v139
	v_add_u32_e32 v134, 0xc3c00, v132
	global_store_dwordx4 v134, v[136:139], s[8:9]
	s_nop 1
	v_mul_f32_e32 v38, v146, v38
	v_mul_f32_e32 v39, v146, v39
	v_mul_f32_e32 v40, v146, v40
	v_mul_f32_e32 v41, v146, v41
	v_mul_f32_e32 v6, v146, v6
	v_mul_f32_e32 v7, v146, v7
	v_mul_f32_e32 v8, v146, v8
	v_mul_f32_e32 v9, v146, v9
	v_cvt_pk_bf16_f32 v136, v38, v39
	v_cvt_pk_bf16_f32 v137, v40, v41
	v_cvt_pk_bf16_f32 v138, v6, v7
	v_cvt_pk_bf16_f32 v139, v8, v9
	s_nop 0
	v_permlane32_swap_b32_e32 v136, v138
	v_permlane32_swap_b32_e32 v137, v139
	s_nop 0
	v_permlane16_swap_b32_e32 v136, v138
	v_permlane16_swap_b32_e32 v137, v139
	v_add_u32_e32 v134, 0xd9800, v132
	global_store_dwordx4 v134, v[136:139], s[8:9]
	s_nop 1
	v_mul_f32_e32 v34, v146, v34
	v_mul_f32_e32 v35, v146, v35
	v_mul_f32_e32 v36, v146, v36
	v_mul_f32_e32 v37, v146, v37
	v_mul_f32_e32 v0, v146, v0
	v_mul_f32_e32 v1, v146, v1
	v_mul_f32_e32 v2, v146, v2
	v_mul_f32_e32 v3, v146, v3
	v_cvt_pk_bf16_f32 v136, v34, v35
	v_cvt_pk_bf16_f32 v137, v36, v37
	v_cvt_pk_bf16_f32 v138, v0, v1
	v_cvt_pk_bf16_f32 v139, v2, v3
	s_nop 0
	v_permlane32_swap_b32_e32 v136, v138
	v_permlane32_swap_b32_e32 v137, v139
	s_nop 0
	v_permlane16_swap_b32_e32 v136, v138
	v_permlane16_swap_b32_e32 v137, v139
	v_add_u32_e32 v134, 0xef400, v132
	global_store_dwordx4 v134, v[136:139], s[8:9]
	s_nop 1
	s_branch .Lipe1_done
; DI u16 f2bf(float x) { unsigned u = __float_as_uint(x); u += 0x7fffu + ((u >> 16) & 1u); return (u16)(u >> 16); }
; DI void phase_inproj(const Params& p, int layer, char* lds) {
;     ...
;           const bool gate = col >= C_GATE;
; #pragma unroll
;           for (int ai = 0; ai < 2; ++ai)
; #pragma unroll
;             for (int m = 0; m < 4; ++m) {
; #pragma unroll
;               for (int j = 0; j < 4; ++j) {
;                 const int row = m0 + ai * 128 + wr8 * 64 + m * 16 + fq * 4 + j;
;                 float v = acc[ai][bj][m][n][j] * sc;
;                 if (gate) v = v * __builtin_amdgcn_rcpf(1.f + __expf(-v));
;                 dst[(size_t)row * dstr + fr] = f2bf(v);
.Lipe1_gate:
	s_mul_i32 s10, s4, 0x15c0
	s_lshl_b32 s11, s25, 1
	s_add_u32 s10, s10, s11
	s_add_u32 s8, s50, s10
	s_addc_u32 s9, s51, 0
	v_mul_f32_e32 v140, 0xbfb8aa3b, v62
	v_mul_f32_e32 v141, 0xbfb8aa3b, v63
	v_mul_f32_e32 v142, 0xbfb8aa3b, v64
	v_mul_f32_e32 v143, 0xbfb8aa3b, v65
	v_exp_f32_e32 v140, v140
	v_exp_f32_e32 v141, v141
	v_exp_f32_e32 v142, v142
	v_exp_f32_e32 v143, v143
	v_add_f32_e32 v140, 1.0, v140
	v_add_f32_e32 v141, 1.0, v141
	v_add_f32_e32 v142, 1.0, v142
	v_add_f32_e32 v143, 1.0, v143
	v_rcp_f32_e32 v140, v140
	v_rcp_f32_e32 v141, v141
	v_rcp_f32_e32 v142, v142
	v_rcp_f32_e32 v143, v143
	v_mul_f32_e32 v62, v62, v140
	v_mul_f32_e32 v63, v63, v141
	v_mul_f32_e32 v64, v64, v142
	v_mul_f32_e32 v65, v65, v143
	v_mul_f32_e32 v140, 0xbfb8aa3b, v30
	v_mul_f32_e32 v141, 0xbfb8aa3b, v31
	v_mul_f32_e32 v142, 0xbfb8aa3b, v32
	v_mul_f32_e32 v143, 0xbfb8aa3b, v33
	v_exp_f32_e32 v140, v140
	v_exp_f32_e32 v141, v141
	v_exp_f32_e32 v142, v142
	v_exp_f32_e32 v143, v143
	v_add_f32_e32 v140, 1.0, v140
	v_add_f32_e32 v141, 1.0, v141
	v_add_f32_e32 v142, 1.0, v142
	v_add_f32_e32 v143, 1.0, v143
	v_rcp_f32_e32 v140, v140
	v_rcp_f32_e32 v141, v141
	v_rcp_f32_e32 v142, v142
	v_rcp_f32_e32 v143, v143
	v_mul_f32_e32 v30, v30, v140
	v_mul_f32_e32 v31, v31, v141
	v_mul_f32_e32 v32, v32, v142
	v_mul_f32_e32 v33, v33, v143
	v_cvt_pk_bf16_f32 v136, v62, v63
	v_cvt_pk_bf16_f32 v137, v64, v65
	v_cvt_pk_bf16_f32 v138, v30, v31
	v_cvt_pk_bf16_f32 v139, v32, v33
	s_nop 0
	v_permlane32_swap_b32_e32 v136, v138
	v_permlane32_swap_b32_e32 v137, v139
	s_nop 0
	v_permlane16_swap_b32_e32 v136, v138
	v_permlane16_swap_b32_e32 v137, v139
	global_store_dwordx4 v132, v[136:139], s[8:9]
	s_nop 1
	v_mul_f32_e32 v140, 0xbfb8aa3b, v58
	v_mul_f32_e32 v141, 0xbfb8aa3b, v59
	v_mul_f32_e32 v142, 0xbfb8aa3b, v60
	v_mul_f32_e32 v143, 0xbfb8aa3b, v61
	v_exp_f32_e32 v140, v140
	v_exp_f32_e32 v141, v141
	v_exp_f32_e32 v142, v142
	v_exp_f32_e32 v143, v143
	v_add_f32_e32 v140, 1.0, v140
	v_add_f32_e32 v141, 1.0, v141
	v_add_f32_e32 v142, 1.0, v142
	v_add_f32_e32 v143, 1.0, v143
	v_rcp_f32_e32 v140, v140
	v_rcp_f32_e32 v141, v141
	v_rcp_f32_e32 v142, v142
	v_rcp_f32_e32 v143, v143
	v_mul_f32_e32 v58, v58, v140
	v_mul_f32_e32 v59, v59, v141
	v_mul_f32_e32 v60, v60, v142
	v_mul_f32_e32 v61, v61, v143
	v_mul_f32_e32 v140, 0xbfb8aa3b, v26
	v_mul_f32_e32 v141, 0xbfb8aa3b, v27
	v_mul_f32_e32 v142, 0xbfb8aa3b, v28
	v_mul_f32_e32 v143, 0xbfb8aa3b, v29
	v_exp_f32_e32 v140, v140
	v_exp_f32_e32 v141, v141
	v_exp_f32_e32 v142, v142
	v_exp_f32_e32 v143, v143
	v_add_f32_e32 v140, 1.0, v140
	v_add_f32_e32 v141, 1.0, v141
	v_add_f32_e32 v142, 1.0, v142
	v_add_f32_e32 v143, 1.0, v143
	v_rcp_f32_e32 v140, v140
	v_rcp_f32_e32 v141, v141
	v_rcp_f32_e32 v142, v142
	v_rcp_f32_e32 v143, v143
	v_mul_f32_e32 v26, v26, v140
	v_mul_f32_e32 v27, v27, v141
	v_mul_f32_e32 v28, v28, v142
	v_mul_f32_e32 v29, v29, v143
	v_cvt_pk_bf16_f32 v136, v58, v59
	v_cvt_pk_bf16_f32 v137, v60, v61
	v_cvt_pk_bf16_f32 v138, v26, v27
	v_cvt_pk_bf16_f32 v139, v28, v29
	s_nop 0
	v_permlane32_swap_b32_e32 v136, v138
	v_permlane32_swap_b32_e32 v137, v139
	s_nop 0
	v_permlane16_swap_b32_e32 v136, v138
	v_permlane16_swap_b32_e32 v137, v139
	v_add_u32_e32 v134, 0x15c00, v132
	global_store_dwordx4 v134, v[136:139], s[8:9]
	s_nop 1
	v_mul_f32_e32 v140, 0xbfb8aa3b, v54
	v_mul_f32_e32 v141, 0xbfb8aa3b, v55
	v_mul_f32_e32 v142, 0xbfb8aa3b, v56
	v_mul_f32_e32 v143, 0xbfb8aa3b, v57
	v_exp_f32_e32 v140, v140
	v_exp_f32_e32 v141, v141
	v_exp_f32_e32 v142, v142
	v_exp_f32_e32 v143, v143
	v_add_f32_e32 v140, 1.0, v140
	v_add_f32_e32 v141, 1.0, v141
	v_add_f32_e32 v142, 1.0, v142
	v_add_f32_e32 v143, 1.0, v143
	v_rcp_f32_e32 v140, v140
	v_rcp_f32_e32 v141, v141
	v_rcp_f32_e32 v142, v142
	v_rcp_f32_e32 v143, v143
	v_mul_f32_e32 v54, v54, v140
	v_mul_f32_e32 v55, v55, v141
	v_mul_f32_e32 v56, v56, v142
	v_mul_f32_e32 v57, v57, v143
	v_mul_f32_e32 v140, 0xbfb8aa3b, v22
	v_mul_f32_e32 v141, 0xbfb8aa3b, v23
	v_mul_f32_e32 v142, 0xbfb8aa3b, v24
	v_mul_f32_e32 v143, 0xbfb8aa3b, v25
	v_exp_f32_e32 v140, v140
	v_exp_f32_e32 v141, v141
	v_exp_f32_e32 v142, v142
	v_exp_f32_e32 v143, v143
	v_add_f32_e32 v140, 1.0, v140
	v_add_f32_e32 v141, 1.0, v141
	v_add_f32_e32 v142, 1.0, v142
	v_add_f32_e32 v143, 1.0, v143
	v_rcp_f32_e32 v140, v140
	v_rcp_f32_e32 v141, v141
	v_rcp_f32_e32 v142, v142
	v_rcp_f32_e32 v143, v143
	v_mul_f32_e32 v22, v22, v140
	v_mul_f32_e32 v23, v23, v141
	v_mul_f32_e32 v24, v24, v142
	v_mul_f32_e32 v25, v25, v143
	v_cvt_pk_bf16_f32 v136, v54, v55
	v_cvt_pk_bf16_f32 v137, v56, v57
	v_cvt_pk_bf16_f32 v138, v22, v23
	v_cvt_pk_bf16_f32 v139, v24, v25
	s_nop 0
	v_permlane32_swap_b32_e32 v136, v138
	v_permlane32_swap_b32_e32 v137, v139
	s_nop 0
	v_permlane16_swap_b32_e32 v136, v138
	v_permlane16_swap_b32_e32 v137, v139
	v_add_u32_e32 v134, 0x2b800, v132
	global_store_dwordx4 v134, v[136:139], s[8:9]
	s_nop 1
	v_mul_f32_e32 v140, 0xbfb8aa3b, v50
	v_mul_f32_e32 v141, 0xbfb8aa3b, v51
	v_mul_f32_e32 v142, 0xbfb8aa3b, v52
	v_mul_f32_e32 v143, 0xbfb8aa3b, v53
	v_exp_f32_e32 v140, v140
	v_exp_f32_e32 v141, v141
	v_exp_f32_e32 v142, v142
	v_exp_f32_e32 v143, v143
	v_add_f32_e32 v140, 1.0, v140
	v_add_f32_e32 v141, 1.0, v141
	v_add_f32_e32 v142, 1.0, v142
	v_add_f32_e32 v143, 1.0, v143
	v_rcp_f32_e32 v140, v140
	v_rcp_f32_e32 v141, v141
	v_rcp_f32_e32 v142, v142
	v_rcp_f32_e32 v143, v143
	v_mul_f32_e32 v50, v50, v140
	v_mul_f32_e32 v51, v51, v141
	v_mul_f32_e32 v52, v52, v142
	v_mul_f32_e32 v53, v53, v143
	v_mul_f32_e32 v140, 0xbfb8aa3b, v18
	v_mul_f32_e32 v141, 0xbfb8aa3b, v19
	v_mul_f32_e32 v142, 0xbfb8aa3b, v20
	v_mul_f32_e32 v143, 0xbfb8aa3b, v21
; DI u16 f2bf(float x) { unsigned u = __float_as_uint(x); u += 0x7fffu + ((u >> 16) & 1u); return (u16)(u >> 16); }
; DI void phase_inproj(const Params& p, int layer, char* lds) {
;     ...
;           const bool gate = col >= C_GATE;
; #pragma unroll
;           for (int ai = 0; ai < 2; ++ai)
; #pragma unroll
;             for (int m = 0; m < 4; ++m) {
; #pragma unroll
;               for (int j = 0; j < 4; ++j) {
;                 const int row = m0 + ai * 128 + wr8 * 64 + m * 16 + fq * 4 + j;
;                 float v = acc[ai][bj][m][n][j] * sc;
;                 if (gate) v = v * __builtin_amdgcn_rcpf(1.f + __expf(-v));
;                 dst[(size_t)row * dstr + fr] = f2bf(v);
	v_exp_f32_e32 v140, v140
	v_exp_f32_e32 v141, v141
	v_exp_f32_e32 v142, v142
	v_exp_f32_e32 v143, v143
	v_add_f32_e32 v140, 1.0, v140
	v_add_f32_e32 v141, 1.0, v141
	v_add_f32_e32 v142, 1.0, v142
	v_add_f32_e32 v143, 1.0, v143
	v_rcp_f32_e32 v140, v140
	v_rcp_f32_e32 v141, v141
	v_rcp_f32_e32 v142, v142
	v_rcp_f32_e32 v143, v143
	v_mul_f32_e32 v18, v18, v140
	v_mul_f32_e32 v19, v19, v141
	v_mul_f32_e32 v20, v20, v142
	v_mul_f32_e32 v21, v21, v143
	v_cvt_pk_bf16_f32 v136, v50, v51
	v_cvt_pk_bf16_f32 v137, v52, v53
	v_cvt_pk_bf16_f32 v138, v18, v19
	v_cvt_pk_bf16_f32 v139, v20, v21
	s_nop 0
	v_permlane32_swap_b32_e32 v136, v138
	v_permlane32_swap_b32_e32 v137, v139
	s_nop 0
	v_permlane16_swap_b32_e32 v136, v138
	v_permlane16_swap_b32_e32 v137, v139
	v_add_u32_e32 v134, 0x41400, v132
	global_store_dwordx4 v134, v[136:139], s[8:9]
	s_nop 1
	v_mul_f32_e32 v140, 0xbfb8aa3b, v46
	v_mul_f32_e32 v141, 0xbfb8aa3b, v47
	v_mul_f32_e32 v142, 0xbfb8aa3b, v48
	v_mul_f32_e32 v143, 0xbfb8aa3b, v49
	v_exp_f32_e32 v140, v140
	v_exp_f32_e32 v141, v141
	v_exp_f32_e32 v142, v142
	v_exp_f32_e32 v143, v143
	v_add_f32_e32 v140, 1.0, v140
	v_add_f32_e32 v141, 1.0, v141
	v_add_f32_e32 v142, 1.0, v142
	v_add_f32_e32 v143, 1.0, v143
	v_rcp_f32_e32 v140, v140
	v_rcp_f32_e32 v141, v141
	v_rcp_f32_e32 v142, v142
	v_rcp_f32_e32 v143, v143
	v_mul_f32_e32 v46, v46, v140
	v_mul_f32_e32 v47, v47, v141
	v_mul_f32_e32 v48, v48, v142
	v_mul_f32_e32 v49, v49, v143
	v_mul_f32_e32 v140, 0xbfb8aa3b, v14
	v_mul_f32_e32 v141, 0xbfb8aa3b, v15
	v_mul_f32_e32 v142, 0xbfb8aa3b, v16
	v_mul_f32_e32 v143, 0xbfb8aa3b, v17
	v_exp_f32_e32 v140, v140
	v_exp_f32_e32 v141, v141
	v_exp_f32_e32 v142, v142
	v_exp_f32_e32 v143, v143
	v_add_f32_e32 v140, 1.0, v140
	v_add_f32_e32 v141, 1.0, v141
	v_add_f32_e32 v142, 1.0, v142
	v_add_f32_e32 v143, 1.0, v143
	v_rcp_f32_e32 v140, v140
	v_rcp_f32_e32 v141, v141
	v_rcp_f32_e32 v142, v142
	v_rcp_f32_e32 v143, v143
	v_mul_f32_e32 v14, v14, v140
	v_mul_f32_e32 v15, v15, v141
	v_mul_f32_e32 v16, v16, v142
	v_mul_f32_e32 v17, v17, v143
	v_cvt_pk_bf16_f32 v136, v46, v47
	v_cvt_pk_bf16_f32 v137, v48, v49
	v_cvt_pk_bf16_f32 v138, v14, v15
	v_cvt_pk_bf16_f32 v139, v16, v17
	s_nop 0
	v_permlane32_swap_b32_e32 v136, v138
	v_permlane32_swap_b32_e32 v137, v139
	s_nop 0
	v_permlane16_swap_b32_e32 v136, v138
	v_permlane16_swap_b32_e32 v137, v139
	v_add_u32_e32 v134, 0xae000, v132
	global_store_dwordx4 v134, v[136:139], s[8:9]
	s_nop 1
	v_mul_f32_e32 v140, 0xbfb8aa3b, v42
	v_mul_f32_e32 v141, 0xbfb8aa3b, v43
	v_mul_f32_e32 v142, 0xbfb8aa3b, v44
	v_mul_f32_e32 v143, 0xbfb8aa3b, v45
	v_exp_f32_e32 v140, v140
	v_exp_f32_e32 v141, v141
	v_exp_f32_e32 v142, v142
	v_exp_f32_e32 v143, v143
	v_add_f32_e32 v140, 1.0, v140
	v_add_f32_e32 v141, 1.0, v141
	v_add_f32_e32 v142, 1.0, v142
	v_add_f32_e32 v143, 1.0, v143
	v_rcp_f32_e32 v140, v140
	v_rcp_f32_e32 v141, v141
	v_rcp_f32_e32 v142, v142
	v_rcp_f32_e32 v143, v143
	v_mul_f32_e32 v42, v42, v140
	v_mul_f32_e32 v43, v43, v141
	v_mul_f32_e32 v44, v44, v142
	v_mul_f32_e32 v45, v45, v143
	v_mul_f32_e32 v140, 0xbfb8aa3b, v10
	v_mul_f32_e32 v141, 0xbfb8aa3b, v11
	v_mul_f32_e32 v142, 0xbfb8aa3b, v12
	v_mul_f32_e32 v143, 0xbfb8aa3b, v13
	v_exp_f32_e32 v140, v140
	v_exp_f32_e32 v141, v141
	v_exp_f32_e32 v142, v142
	v_exp_f32_e32 v143, v143
	v_add_f32_e32 v140, 1.0, v140
	v_add_f32_e32 v141, 1.0, v141
	v_add_f32_e32 v142, 1.0, v142
	v_add_f32_e32 v143, 1.0, v143
	v_rcp_f32_e32 v140, v140
	v_rcp_f32_e32 v141, v141
	v_rcp_f32_e32 v142, v142
	v_rcp_f32_e32 v143, v143
	v_mul_f32_e32 v10, v10, v140
	v_mul_f32_e32 v11, v11, v141
	v_mul_f32_e32 v12, v12, v142
; DI u16 f2bf(float x) { unsigned u = __float_as_uint(x); u += 0x7fffu + ((u >> 16) & 1u); return (u16)(u >> 16); }
; DI void phase_inproj(const Params& p, int layer, char* lds) {
;     ...
;           const bool gate = col >= C_GATE;
; #pragma unroll
;           for (int ai = 0; ai < 2; ++ai)
; #pragma unroll
;             for (int m = 0; m < 4; ++m) {
; #pragma unroll
;               for (int j = 0; j < 4; ++j) {
;                 const int row = m0 + ai * 128 + wr8 * 64 + m * 16 + fq * 4 + j;
;                 float v = acc[ai][bj][m][n][j] * sc;
;                 if (gate) v = v * __builtin_amdgcn_rcpf(1.f + __expf(-v));
;                 dst[(size_t)row * dstr + fr] = f2bf(v);
	v_mul_f32_e32 v13, v13, v143
	v_cvt_pk_bf16_f32 v136, v42, v43
	v_cvt_pk_bf16_f32 v137, v44, v45
	v_cvt_pk_bf16_f32 v138, v10, v11
	v_cvt_pk_bf16_f32 v139, v12, v13
	s_nop 0
	v_permlane32_swap_b32_e32 v136, v138
	v_permlane32_swap_b32_e32 v137, v139
	s_nop 0
	v_permlane16_swap_b32_e32 v136, v138
	v_permlane16_swap_b32_e32 v137, v139
	v_add_u32_e32 v134, 0xc3c00, v132
	global_store_dwordx4 v134, v[136:139], s[8:9]
	s_nop 1
	v_mul_f32_e32 v140, 0xbfb8aa3b, v38
	v_mul_f32_e32 v141, 0xbfb8aa3b, v39
	v_mul_f32_e32 v142, 0xbfb8aa3b, v40
	v_mul_f32_e32 v143, 0xbfb8aa3b, v41
	v_exp_f32_e32 v140, v140
	v_exp_f32_e32 v141, v141
	v_exp_f32_e32 v142, v142
	v_exp_f32_e32 v143, v143
	v_add_f32_e32 v140, 1.0, v140
	v_add_f32_e32 v141, 1.0, v141
	v_add_f32_e32 v142, 1.0, v142
	v_add_f32_e32 v143, 1.0, v143
	v_rcp_f32_e32 v140, v140
	v_rcp_f32_e32 v141, v141
	v_rcp_f32_e32 v142, v142
	v_rcp_f32_e32 v143, v143
	v_mul_f32_e32 v38, v38, v140
	v_mul_f32_e32 v39, v39, v141
	v_mul_f32_e32 v40, v40, v142
	v_mul_f32_e32 v41, v41, v143
	v_mul_f32_e32 v140, 0xbfb8aa3b, v6
	v_mul_f32_e32 v141, 0xbfb8aa3b, v7
	v_mul_f32_e32 v142, 0xbfb8aa3b, v8
	v_mul_f32_e32 v143, 0xbfb8aa3b, v9
	v_exp_f32_e32 v140, v140
	v_exp_f32_e32 v141, v141
	v_exp_f32_e32 v142, v142
	v_exp_f32_e32 v143, v143
	v_add_f32_e32 v140, 1.0, v140
	v_add_f32_e32 v141, 1.0, v141
	v_add_f32_e32 v142, 1.0, v142
	v_add_f32_e32 v143, 1.0, v143
	v_rcp_f32_e32 v140, v140
	v_rcp_f32_e32 v141, v141
	v_rcp_f32_e32 v142, v142
	v_rcp_f32_e32 v143, v143
	v_mul_f32_e32 v6, v6, v140
	v_mul_f32_e32 v7, v7, v141
	v_mul_f32_e32 v8, v8, v142
	v_mul_f32_e32 v9, v9, v143
	v_cvt_pk_bf16_f32 v136, v38, v39
	v_cvt_pk_bf16_f32 v137, v40, v41
	v_cvt_pk_bf16_f32 v138, v6, v7
	v_cvt_pk_bf16_f32 v139, v8, v9
	s_nop 0
	v_permlane32_swap_b32_e32 v136, v138
	v_permlane32_swap_b32_e32 v137, v139
	s_nop 0
	v_permlane16_swap_b32_e32 v136, v138
	v_permlane16_swap_b32_e32 v137, v139
	v_add_u32_e32 v134, 0xd9800, v132
	global_store_dwordx4 v134, v[136:139], s[8:9]
	s_nop 1
	v_mul_f32_e32 v140, 0xbfb8aa3b, v34
	v_mul_f32_e32 v141, 0xbfb8aa3b, v35
	v_mul_f32_e32 v142, 0xbfb8aa3b, v36
	v_mul_f32_e32 v143, 0xbfb8aa3b, v37
	v_exp_f32_e32 v140, v140
	v_exp_f32_e32 v141, v141
	v_exp_f32_e32 v142, v142
	v_exp_f32_e32 v143, v143
	v_add_f32_e32 v140, 1.0, v140
	v_add_f32_e32 v141, 1.0, v141
	v_add_f32_e32 v142, 1.0, v142
	v_add_f32_e32 v143, 1.0, v143
	v_rcp_f32_e32 v140, v140
	v_rcp_f32_e32 v141, v141
	v_rcp_f32_e32 v142, v142
	v_rcp_f32_e32 v143, v143
	v_mul_f32_e32 v34, v34, v140
	v_mul_f32_e32 v35, v35, v141
	v_mul_f32_e32 v36, v36, v142
	v_mul_f32_e32 v37, v37, v143
	v_mul_f32_e32 v140, 0xbfb8aa3b, v0
	v_mul_f32_e32 v141, 0xbfb8aa3b, v1
	v_mul_f32_e32 v142, 0xbfb8aa3b, v2
	v_mul_f32_e32 v143, 0xbfb8aa3b, v3
	v_exp_f32_e32 v140, v140
	v_exp_f32_e32 v141, v141
	v_exp_f32_e32 v142, v142
	v_exp_f32_e32 v143, v143
	v_add_f32_e32 v140, 1.0, v140
	v_add_f32_e32 v141, 1.0, v141
	v_add_f32_e32 v142, 1.0, v142
	v_add_f32_e32 v143, 1.0, v143
	v_rcp_f32_e32 v140, v140
	v_rcp_f32_e32 v141, v141
	v_rcp_f32_e32 v142, v142
	v_rcp_f32_e32 v143, v143
	v_mul_f32_e32 v0, v0, v140
	v_mul_f32_e32 v1, v1, v141
	v_mul_f32_e32 v2, v2, v142
	v_mul_f32_e32 v3, v3, v143
	v_cvt_pk_bf16_f32 v136, v34, v35
	v_cvt_pk_bf16_f32 v137, v36, v37
	v_cvt_pk_bf16_f32 v138, v0, v1
	v_cvt_pk_bf16_f32 v139, v2, v3
	s_nop 0
	v_permlane32_swap_b32_e32 v136, v138
	v_permlane32_swap_b32_e32 v137, v139
	s_nop 0
	v_permlane16_swap_b32_e32 v136, v138
	v_permlane16_swap_b32_e32 v137, v139
	v_add_u32_e32 v134, 0xef400, v132
	global_store_dwordx4 v134, v[136:139], s[8:9]
	s_nop 1
	s_branch .Lipe1_done

; DI u16 f2bf(float x) { unsigned u = __float_as_uint(x); u += 0x7fffu + ((u >> 16) & 1u); return (u16)(u >> 16); }
; DI void phase_inproj(const Params& p, int layer, char* lds) {
;     ...
;           if (cw >= C_DK && cw < C_DV) { const int o = cw - C_DK; dst = (u16*)(p.ws + OFF_DK) + ((size_t)(bb * 3 * S + (o >> 6) * S) << 6) + (o & 63); dstr = 64; }
;           else if (cw >= C_DV && cw < C_SQ) { const int o = cw - C_DV; dst = (u16*)(p.ws + OFF_DV) + ((size_t)(bb * 3 * S + (o >> 6) * S) << 6) + (o & 63); dstr = 64; }
;           else if (cw >= C_SK && cw < C_SV) { const int o = cw - C_SK; dst = (u16*)(p.ws + OFF_SK) + ((size_t)(bb * 1 * S + (o >> 6) * S) << 6) + (o & 63); dstr = 64; }
;           else if (cw >= C_SV && cw < C_GATE) { const int o = cw - C_SV; dst = (u16*)(p.ws + OFF_SV) + ((size_t)(bb * 1 * S + (o >> 6) * S) << 6) + (o & 63); dstr = 64; }
;         }
;         if (cw < DIN) {
;           float sc = 1.f;
;           if (col >= C_DQ && col < C_DK) sc = SC_DQ;
;           if (col >= C_SQ && col < C_SK) sc = SC_SQ;
;           const bool gate = col >= C_GATE;
; #pragma unroll
;           for (int ai = 0; ai < 2; ++ai)
; #pragma unroll
;             for (int m = 0; m < 4; ++m) {
; #pragma unroll
;               for (int j = 0; j < 4; ++j) {
;                 const int row = m0 + ai * 128 + wr8 * 64 + m * 16 + fq * 4 + j;
;                 float v = acc[ai][bj][m][n][j] * sc;
;                 if (gate) v = v * __builtin_amdgcn_rcpf(1.f + __expf(-v));
;                 dst[(size_t)row * dstr + fr] = f2bf(v);
.Lipe1_kv:
	v_cvt_pk_bf16_f32 v136, v62, v63
	v_cvt_pk_bf16_f32 v137, v64, v65
	v_cvt_pk_bf16_f32 v138, v30, v31
	v_cvt_pk_bf16_f32 v139, v32, v33
	s_nop 0
	v_permlane32_swap_b32_e32 v136, v138
	v_permlane32_swap_b32_e32 v137, v139
	s_nop 0
	v_permlane16_swap_b32_e32 v136, v138
	v_permlane16_swap_b32_e32 v137, v139
	global_store_dwordx4 v133, v[136:139], s[8:9]
	s_nop 1
	v_cvt_pk_bf16_f32 v136, v58, v59
	v_cvt_pk_bf16_f32 v137, v60, v61
	v_cvt_pk_bf16_f32 v138, v26, v27
	v_cvt_pk_bf16_f32 v139, v28, v29
	s_nop 0
	v_permlane32_swap_b32_e32 v136, v138
	v_permlane32_swap_b32_e32 v137, v139
	s_nop 0
	v_permlane16_swap_b32_e32 v136, v138
	v_permlane16_swap_b32_e32 v137, v139
	v_add_u32_e32 v134, 0x800, v133
	global_store_dwordx4 v134, v[136:139], s[8:9]
	s_nop 1
	v_cvt_pk_bf16_f32 v136, v54, v55
	v_cvt_pk_bf16_f32 v137, v56, v57
	v_cvt_pk_bf16_f32 v138, v22, v23
	v_cvt_pk_bf16_f32 v139, v24, v25
	s_nop 0
	v_permlane32_swap_b32_e32 v136, v138
	v_permlane32_swap_b32_e32 v137, v139
	s_nop 0
	v_permlane16_swap_b32_e32 v136, v138
	v_permlane16_swap_b32_e32 v137, v139
	v_add_u32_e32 v134, 0x1000, v133
	global_store_dwordx4 v134, v[136:139], s[8:9]
	s_nop 1
	v_cvt_pk_bf16_f32 v136, v50, v51
	v_cvt_pk_bf16_f32 v137, v52, v53
	v_cvt_pk_bf16_f32 v138, v18, v19
	v_cvt_pk_bf16_f32 v139, v20, v21
	s_nop 0
	v_permlane32_swap_b32_e32 v136, v138
	v_permlane32_swap_b32_e32 v137, v139
	s_nop 0
	v_permlane16_swap_b32_e32 v136, v138
	v_permlane16_swap_b32_e32 v137, v139
	v_add_u32_e32 v134, 0x1800, v133
	global_store_dwordx4 v134, v[136:139], s[8:9]
	s_nop 1
	v_cvt_pk_bf16_f32 v136, v46, v47
	v_cvt_pk_bf16_f32 v137, v48, v49
	v_cvt_pk_bf16_f32 v138, v14, v15
	v_cvt_pk_bf16_f32 v139, v16, v17
	s_nop 0
	v_permlane32_swap_b32_e32 v136, v138
	v_permlane32_swap_b32_e32 v137, v139
	s_nop 0
	v_permlane16_swap_b32_e32 v136, v138
	v_permlane16_swap_b32_e32 v137, v139
	v_add_u32_e32 v134, 0x4000, v133
	global_store_dwordx4 v134, v[136:139], s[8:9]
	s_nop 1
	v_cvt_pk_bf16_f32 v136, v42, v43
	v_cvt_pk_bf16_f32 v137, v44, v45
	v_cvt_pk_bf16_f32 v138, v10, v11
	v_cvt_pk_bf16_f32 v139, v12, v13
	s_nop 0
	v_permlane32_swap_b32_e32 v136, v138
	v_permlane32_swap_b32_e32 v137, v139
	s_nop 0
	v_permlane16_swap_b32_e32 v136, v138
	v_permlane16_swap_b32_e32 v137, v139
	v_add_u32_e32 v134, 0x4800, v133
	global_store_dwordx4 v134, v[136:139], s[8:9]
	s_nop 1
	v_cvt_pk_bf16_f32 v136, v38, v39
	v_cvt_pk_bf16_f32 v137, v40, v41
	v_cvt_pk_bf16_f32 v138, v6, v7
	v_cvt_pk_bf16_f32 v139, v8, v9
	s_nop 0
	v_permlane32_swap_b32_e32 v136, v138
	v_permlane32_swap_b32_e32 v137, v139
	s_nop 0
	v_permlane16_swap_b32_e32 v136, v138
	v_permlane16_swap_b32_e32 v137, v139
	v_add_u32_e32 v134, 0x5000, v133
	global_store_dwordx4 v134, v[136:139], s[8:9]
	s_nop 1
	v_cvt_pk_bf16_f32 v136, v34, v35
	v_cvt_pk_bf16_f32 v137, v36, v37
	v_cvt_pk_bf16_f32 v138, v0, v1
	v_cvt_pk_bf16_f32 v139, v2, v3
	s_nop 0
	v_permlane32_swap_b32_e32 v136, v138
	v_permlane32_swap_b32_e32 v137, v139
	s_nop 0
	v_permlane16_swap_b32_e32 v136, v138
	v_permlane16_swap_b32_e32 v137, v139
	v_add_u32_e32 v134, 0x5800, v133
	global_store_dwordx4 v134, v[136:139], s[8:9]
	s_nop 1
